# attn_sample: third pass of each key loop (single live key) takes a one-key path instead of loading and reducing sixteen masked keys
# speedup vs baseline: 1.0188x; 1.0048x over previous
; __device__ __forceinline__ void attn_sample(const Params& p, int j, LAS unsigned char* lds, int gw, int NGW, int wave, int lane) {
;     ...
;             for (int jj0 = 0; jj0 < 129; jj0 += 64) {
;                 f32x4 kv[16];
; #pragma unroll
;                 for (int u = 0; u < 16; ++u) { int jj = jj0 + u * 4 + rs; jj = jj > 128 ? 128 : jj; const int pos = W + t - (jj << dsh);
;                     kv[u] = *(const f32x4*)(pos >= W ? nbuf + (size_t)(pos - 8) * 1024 : cache + (size_t)pos * 1024); }
; #pragma unroll
;                 for (int u = 0; u < 16; ++u) { const int jj = jj0 + u * 4 + rs;
;                     const float d = row16_sum(kv[u][0] * qv[g][0] + kv[u][1] * qv[g][1] + kv[u][2] * qv[g][2] + kv[u][3] * qv[g][3]);
;                     if (jj <= 128) { mx = fmaxf(mx, d); if (ch == 0) scs[g * 129 + jj] = d; } }
.LBB0_328:
	v_add_u32_e32 v79, s42, v65
	v_add_u32_e32 v78, 64, v79
	v_min_i32_e32 v0, 0x80, v78
	v_sub_u32_e32 v0, s34, v0
	v_add_u32_e32 v1, -8, v0
	v_cmp_gt_i32_e32 vcc, s78, v0
	v_mov_b32_e32 v80, 0
	s_nop 0
	v_cndmask_b32_e32 v184, v1, v0, vcc
	v_cndmask_b32_e32 v1, v77, v71, vcc
	v_cndmask_b32_e32 v0, v76, v70, vcc
	v_lshlrev_b64 v[2:3], 12, v[184:185]
	v_lshl_add_u64 v[0:1], v[0:1], 0, v[2:3]
	global_load_dwordx4 v[92:95], v[0:1], off
	s_cmp_eq_u32 s42, 64
	s_cbranch_scc1 .Las_k0_mini
	v_add_u32_e32 v0, 0x44, v79
	v_min_i32_e32 v0, 0x80, v0
	v_sub_u32_e32 v0, s34, v0
	v_add_u32_e32 v1, -8, v0
	v_cmp_gt_i32_e32 vcc, s78, v0
	s_nop 1
	v_cndmask_b32_e32 v184, v1, v0, vcc
	v_cndmask_b32_e32 v1, v77, v71, vcc
	v_cndmask_b32_e32 v0, v76, v70, vcc
	v_lshlrev_b64 v[2:3], 12, v[184:185]
	v_lshl_add_u64 v[0:1], v[0:1], 0, v[2:3]
	global_load_dwordx4 v[56:59], v[0:1], off
	v_add_u32_e32 v0, 0x48, v79
	v_min_i32_e32 v0, 0x80, v0
	v_sub_u32_e32 v0, s34, v0
	v_add_u32_e32 v1, -8, v0
	v_cmp_gt_i32_e32 vcc, s78, v0
	s_nop 1
	v_cndmask_b32_e32 v184, v1, v0, vcc
	v_cndmask_b32_e32 v1, v77, v71, vcc
	v_cndmask_b32_e32 v0, v76, v70, vcc
	v_lshlrev_b64 v[2:3], 12, v[184:185]
	v_lshl_add_u64 v[0:1], v[0:1], 0, v[2:3]
	global_load_dwordx4 v[52:55], v[0:1], off
	v_add_u32_e32 v0, 0x4c, v79
	v_min_i32_e32 v0, 0x80, v0
	v_sub_u32_e32 v0, s34, v0
	v_add_u32_e32 v1, -8, v0
	v_cmp_gt_i32_e32 vcc, s78, v0
	s_nop 1
	v_cndmask_b32_e32 v184, v1, v0, vcc
	v_cndmask_b32_e32 v1, v77, v71, vcc
	v_cndmask_b32_e32 v0, v76, v70, vcc
	v_lshlrev_b64 v[2:3], 12, v[184:185]
	v_lshl_add_u64 v[0:1], v[0:1], 0, v[2:3]
	global_load_dwordx4 v[48:51], v[0:1], off
	v_add_u32_e32 v0, 0x50, v79
	v_min_i32_e32 v0, 0x80, v0
	v_sub_u32_e32 v0, s34, v0
	v_add_u32_e32 v1, -8, v0
	v_cmp_gt_i32_e32 vcc, s78, v0
	s_nop 1
	v_cndmask_b32_e32 v184, v1, v0, vcc
	v_cndmask_b32_e32 v1, v77, v71, vcc
	v_cndmask_b32_e32 v0, v76, v70, vcc
	v_lshlrev_b64 v[2:3], 12, v[184:185]
	v_lshl_add_u64 v[0:1], v[0:1], 0, v[2:3]
	global_load_dwordx4 v[44:47], v[0:1], off
	v_add_u32_e32 v0, 0x54, v79
	v_min_i32_e32 v0, 0x80, v0
	v_sub_u32_e32 v0, s34, v0
	v_add_u32_e32 v1, -8, v0
	v_cmp_gt_i32_e32 vcc, s78, v0
	s_nop 1
	v_cndmask_b32_e32 v184, v1, v0, vcc
	v_cndmask_b32_e32 v1, v77, v71, vcc
	v_cndmask_b32_e32 v0, v76, v70, vcc
	v_lshlrev_b64 v[2:3], 12, v[184:185]
	v_lshl_add_u64 v[0:1], v[0:1], 0, v[2:3]
	global_load_dwordx4 v[40:43], v[0:1], off
	v_add_u32_e32 v0, 0x58, v79
	v_min_i32_e32 v0, 0x80, v0
	v_sub_u32_e32 v0, s34, v0
	v_add_u32_e32 v1, -8, v0
	v_cmp_gt_i32_e32 vcc, s78, v0
	s_nop 1
	v_cndmask_b32_e32 v184, v1, v0, vcc
	v_cndmask_b32_e32 v1, v77, v71, vcc
	v_cndmask_b32_e32 v0, v76, v70, vcc
	v_lshlrev_b64 v[2:3], 12, v[184:185]
	v_lshl_add_u64 v[0:1], v[0:1], 0, v[2:3]
	global_load_dwordx4 v[36:39], v[0:1], off
	v_add_u32_e32 v0, 0x5c, v79
	v_min_i32_e32 v0, 0x80, v0
	v_sub_u32_e32 v0, s34, v0
	v_add_u32_e32 v1, -8, v0
	v_cmp_gt_i32_e32 vcc, s78, v0
	s_nop 1
	v_cndmask_b32_e32 v184, v1, v0, vcc
	v_cndmask_b32_e32 v1, v77, v71, vcc
	v_cndmask_b32_e32 v0, v76, v70, vcc
	v_lshlrev_b64 v[2:3], 12, v[184:185]
	v_lshl_add_u64 v[0:1], v[0:1], 0, v[2:3]
	global_load_dwordx4 v[32:35], v[0:1], off
	v_add_u32_e32 v0, 0x60, v79
	v_min_i32_e32 v0, 0x80, v0
	v_sub_u32_e32 v0, s34, v0
	v_add_u32_e32 v1, -8, v0
	v_cmp_gt_i32_e32 vcc, s78, v0
	s_nop 1
	v_cndmask_b32_e32 v184, v1, v0, vcc
	v_cndmask_b32_e32 v1, v77, v71, vcc
	v_cndmask_b32_e32 v0, v76, v70, vcc
	v_lshlrev_b64 v[2:3], 12, v[184:185]
	v_lshl_add_u64 v[0:1], v[0:1], 0, v[2:3]
	global_load_dwordx4 v[28:31], v[0:1], off
	v_add_u32_e32 v0, 0x64, v79
	v_min_i32_e32 v0, 0x80, v0
	v_sub_u32_e32 v0, s34, v0
	v_add_u32_e32 v1, -8, v0
	v_cmp_gt_i32_e32 vcc, s78, v0
	s_nop 1
	v_cndmask_b32_e32 v184, v1, v0, vcc
	v_cndmask_b32_e32 v1, v77, v71, vcc
	v_cndmask_b32_e32 v0, v76, v70, vcc
	v_lshlrev_b64 v[2:3], 12, v[184:185]
	v_lshl_add_u64 v[0:1], v[0:1], 0, v[2:3]
	global_load_dwordx4 v[24:27], v[0:1], off
	v_add_u32_e32 v0, 0x68, v79
	v_min_i32_e32 v0, 0x80, v0
	v_sub_u32_e32 v0, s34, v0
	v_add_u32_e32 v1, -8, v0
	v_cmp_gt_i32_e32 vcc, s78, v0
	s_nop 1
	v_cndmask_b32_e32 v184, v1, v0, vcc
	v_cndmask_b32_e32 v1, v77, v71, vcc
	v_cndmask_b32_e32 v0, v76, v70, vcc
	v_lshlrev_b64 v[2:3], 12, v[184:185]
	v_lshl_add_u64 v[0:1], v[0:1], 0, v[2:3]
	global_load_dwordx4 v[20:23], v[0:1], off
	v_add_u32_e32 v0, 0x6c, v79
	v_min_i32_e32 v0, 0x80, v0
	v_sub_u32_e32 v0, s34, v0
	v_add_u32_e32 v1, -8, v0
	v_cmp_gt_i32_e32 vcc, s78, v0
	s_nop 1
	v_cndmask_b32_e32 v184, v1, v0, vcc
	v_cndmask_b32_e32 v1, v77, v71, vcc
	v_cndmask_b32_e32 v0, v76, v70, vcc
	v_lshlrev_b64 v[2:3], 12, v[184:185]
	v_lshl_add_u64 v[0:1], v[0:1], 0, v[2:3]
	global_load_dwordx4 v[16:19], v[0:1], off
	v_add_u32_e32 v0, 0x70, v79
	v_min_i32_e32 v0, 0x80, v0
	v_sub_u32_e32 v0, s34, v0
	v_add_u32_e32 v1, -8, v0
	v_cmp_gt_i32_e32 vcc, s78, v0
	s_nop 1
	v_cndmask_b32_e32 v184, v1, v0, vcc
	v_cndmask_b32_e32 v1, v77, v71, vcc
	v_cndmask_b32_e32 v0, v76, v70, vcc
	v_lshlrev_b64 v[2:3], 12, v[184:185]
	v_lshl_add_u64 v[0:1], v[0:1], 0, v[2:3]
	global_load_dwordx4 v[12:15], v[0:1], off
	v_add_u32_e32 v0, 0x74, v79
	v_min_i32_e32 v0, 0x80, v0
	v_sub_u32_e32 v0, s34, v0
	v_add_u32_e32 v1, -8, v0
	v_cmp_gt_i32_e32 vcc, s78, v0
	s_nop 1
	v_cndmask_b32_e32 v184, v1, v0, vcc
	v_cndmask_b32_e32 v1, v77, v71, vcc
	v_cndmask_b32_e32 v0, v76, v70, vcc
	v_lshlrev_b64 v[2:3], 12, v[184:185]
	v_lshl_add_u64 v[0:1], v[0:1], 0, v[2:3]
	global_load_dwordx4 v[8:11], v[0:1], off
	v_add_u32_e32 v0, 0x78, v79
	v_min_i32_e32 v0, 0x80, v0
	v_sub_u32_e32 v0, s34, v0
	v_add_u32_e32 v1, -8, v0
	v_cmp_gt_i32_e32 vcc, s78, v0
	s_nop 1
	v_cndmask_b32_e32 v184, v1, v0, vcc
	v_cndmask_b32_e32 v1, v77, v71, vcc
	v_cndmask_b32_e32 v0, v76, v70, vcc
	v_lshlrev_b64 v[2:3], 12, v[184:185]
	v_lshl_add_u64 v[0:1], v[0:1], 0, v[2:3]
	global_load_dwordx4 v[4:7], v[0:1], off
	v_add_u32_e32 v0, 0x7c, v79
	v_min_i32_e32 v0, 0x80, v0
	v_sub_u32_e32 v0, s34, v0
	v_add_u32_e32 v1, -8, v0
	v_cmp_gt_i32_e32 vcc, s78, v0
	s_waitcnt vmcnt(14)
	v_mul_f32_e32 v79, v63, v93
	v_fmac_f32_e32 v79, v62, v92
	v_cndmask_b32_e32 v184, v1, v0, vcc
	v_cndmask_b32_e32 v1, v77, v71, vcc
	v_cndmask_b32_e32 v0, v76, v70, vcc
	v_lshlrev_b64 v[2:3], 12, v[184:185]
	v_lshl_add_u64 v[0:1], v[0:1], 0, v[2:3]
	global_load_dwordx4 v[0:3], v[0:1], off
	v_fmac_f32_e32 v79, v60, v94
	v_fmac_f32_e32 v79, v61, v95
	v_cmp_gt_i32_e32 vcc, s35, v78
	s_nop 0
	v_add_f32_dpp v79, v79, v79 row_ror:8 row_mask:0xf bank_mask:0xf bound_ctrl:1
	s_nop 1
	v_add_f32_dpp v79, v79, v79 row_ror:4 row_mask:0xf bank_mask:0xf bound_ctrl:1
	s_nop 1
	v_add_f32_dpp v79, v79, v79 row_ror:2 row_mask:0xf bank_mask:0xf bound_ctrl:1
	s_nop 1
	v_mov_b32_dpp v80, v79 row_ror:1 row_mask:0xf bank_mask:0xf
	s_and_saveexec_b64 s[12:13], vcc
	s_cbranch_execz .LBB0_332
	v_add_f32_e32 v79, v79, v80
	s_and_saveexec_b64 s[30:31], s[36:37]
	ds_write_b32 v69, v79
	s_or_b64 exec, exec, s[30:31]
	v_max_f32_e32 v67, v67, v67
	v_max_f32_e32 v67, v67, v79

; __device__ __forceinline__ void attn_sample(const Params& p, int j, LAS unsigned char* lds, int gw, int NGW, int wave, int lane) {
;     ...
;                 for (int u = 0; u < 16; ++u) { int jj = jj0 + u * 4 + rs; jj = jj > 128 ? 128 : jj; const int pos = W + t - (jj << dsh);
;                     kv[u] = *(const f32x4*)(pos >= W ? nbuf + (size_t)(pos - 8) * 1024 : cache + (size_t)pos * 1024); }
; #pragma unroll
;                 for (int u = 0; u < 16; ++u) { const int jj = jj0 + u * 4 + rs;
;                     const float d = row16_sum(kv[u][0] * qv[g][0] + kv[u][1] * qv[g][1] + kv[u][2] * qv[g][2] + kv[u][3] * qv[g][3]);
;                     if (jj <= 128) { mx = fmaxf(mx, d); if (ch == 0) scs[g * 129 + jj] = d; } }
.Las_k0_mini:
	s_waitcnt vmcnt(0)
	v_mul_f32_e32 v79, v63, v93
	v_fmac_f32_e32 v79, v62, v92
	v_fmac_f32_e32 v79, v60, v94
	v_fmac_f32_e32 v79, v61, v95
	v_cmp_gt_i32_e32 vcc, s35, v78
	s_nop 0
	v_add_f32_dpp v79, v79, v79 row_ror:8 row_mask:0xf bank_mask:0xf bound_ctrl:1
	s_nop 1
	v_add_f32_dpp v79, v79, v79 row_ror:4 row_mask:0xf bank_mask:0xf bound_ctrl:1
	s_nop 1
	v_add_f32_dpp v79, v79, v79 row_ror:2 row_mask:0xf bank_mask:0xf bound_ctrl:1
	s_nop 1
	v_mov_b32_dpp v80, v79 row_ror:1 row_mask:0xf bank_mask:0xf
	s_and_saveexec_b64 s[12:13], vcc
	s_cbranch_execz .Las_k0_skip
	v_add_f32_e32 v79, v79, v80
	s_and_saveexec_b64 s[30:31], s[36:37]
	ds_write_b32 v69, v79
	s_or_b64 exec, exec, s[30:31]
	v_max_f32_e32 v67, v67, v67
	v_max_f32_e32 v67, v67, v79
.Las_k0_skip:
	s_branch .LBB0_327
.Las_k1_mini:
	s_waitcnt vmcnt(0)
	v_mul_f32_e32 v61, v79, v61
	v_fmac_f32_e32 v61, v78, v60
	v_fmac_f32_e32 v61, v76, v62
	v_fmac_f32_e32 v61, v77, v63
	v_cmp_gt_i32_e32 vcc, s35, v82
	s_nop 0
	v_add_f32_dpp v60, v61, v61 row_ror:8 row_mask:0xf bank_mask:0xf bound_ctrl:1
	v_mov_b32_e32 v61, 0
	s_nop 0
	v_add_f32_dpp v60, v60, v60 row_ror:4 row_mask:0xf bank_mask:0xf bound_ctrl:1
	s_nop 1
	v_add_f32_dpp v60, v60, v60 row_ror:2 row_mask:0xf bank_mask:0xf bound_ctrl:1
	s_nop 1
	v_mov_b32_dpp v61, v60 row_ror:1 row_mask:0xf bank_mask:0xf
	s_and_saveexec_b64 s[30:31], vcc
	s_cbranch_execz .Las_k1_skip
	v_add_f32_e32 v60, v60, v61
	s_and_saveexec_b64 s[42:43], s[36:37]
	ds_write_b32 v69, v60
	s_or_b64 exec, exec, s[42:43]
	v_max_f32_e32 v61, v67, v67
	v_max_f32_e32 v67, v61, v60

; __device__ __forceinline__ void attn_sample(const Params& p, int j, LAS unsigned char* lds, int gw, int NGW, int wave, int lane) {
;     ...
;                 for (int u = 0; u < 16; ++u) { int jj = jj0 + u * 4 + rs; jj = jj > 128 ? 128 : jj; const int pos = W + t - (jj << dsh);
;                     kv[u] = *(const f32x4*)(pos >= W ? nbuf + (size_t)(pos - 8) * 1024 : cache + (size_t)pos * 1024); }
; #pragma unroll
;                 for (int u = 0; u < 16; ++u) { const int jj = jj0 + u * 4 + rs;
;                     const float d = row16_sum(kv[u][0] * qv[g][0] + kv[u][1] * qv[g][1] + kv[u][2] * qv[g][2] + kv[u][3] * qv[g][3]);
;                     if (jj <= 128) { mx = fmaxf(mx, d); if (ch == 0) scs[g * 129 + jj] = d; } }
.Las_k2_mini:
	s_waitcnt vmcnt(0)
	v_mul_f32_e32 v61, v79, v61
	v_fmac_f32_e32 v61, v78, v60
	v_fmac_f32_e32 v61, v76, v62
	v_fmac_f32_e32 v61, v77, v63
	v_cmp_gt_i32_e32 vcc, s35, v82
	s_nop 0
	v_add_f32_dpp v60, v61, v61 row_ror:8 row_mask:0xf bank_mask:0xf bound_ctrl:1
	v_mov_b32_e32 v61, 0
	s_nop 0
	v_add_f32_dpp v60, v60, v60 row_ror:4 row_mask:0xf bank_mask:0xf bound_ctrl:1
	s_nop 1
	v_add_f32_dpp v60, v60, v60 row_ror:2 row_mask:0xf bank_mask:0xf bound_ctrl:1
	s_nop 1
	v_mov_b32_dpp v61, v60 row_ror:1 row_mask:0xf bank_mask:0xf
	s_and_saveexec_b64 s[24:25], vcc
	s_cbranch_execz .Las_k2_skip
	v_add_f32_e32 v60, v60, v61
	s_and_saveexec_b64 s[30:31], s[36:37]
	ds_write_b32 v69, v60
	s_or_b64 exec, exec, s[30:31]
	v_max_f32_e32 v61, v67, v67
	v_max_f32_e32 v67, v61, v60

; __device__ __forceinline__ void attn_sample(const Params& p, int j, LAS unsigned char* lds, int gw, int NGW, int wave, int lane) {
;     ...
;                 for (int u = 0; u < 16; ++u) { int jj = jj0 + u * 4 + rs; const bool ok = jj <= 128; jj = ok ? jj : 128; const int pos = W + t - (jj << dsh);
;                     vv[u] = *(const f32x4*)(pos >= W ? nbuf + (size_t)(pos - 8) * 1024 : cache + (size_t)pos * 1024);
;                     pj[u] = ok ? scs[g * 129 + jj] : 0.f; }
; #pragma unroll
;                 for (int u = 0; u < 16; ++u) acc += vv[u] * pj[u];
.Las_v0_mini:
	s_waitcnt vmcnt(0) lgkmcnt(0)
	v_pk_fma_f32 v[70:71], v[2:3], v[82:83], v[70:71] op_sel_hi:[1,0,1]
	v_pk_fma_f32 v[76:77], v[0:1], v[82:83], v[76:77] op_sel_hi:[1,0,1]
	s_add_i32 s26, s26, 64
	v_add_u32_e32 v69, 0x100, v69
	s_branch .LBB0_561
.Las_v1_mini:
	s_waitcnt vmcnt(0) lgkmcnt(0)
	v_pk_fma_f32 v[70:71], v[2:3], v[82:83], v[70:71] op_sel_hi:[1,0,1]
	v_pk_fma_f32 v[76:77], v[0:1], v[82:83], v[76:77] op_sel_hi:[1,0,1]
	s_add_i32 s24, s24, 64
	v_add_u32_e32 v69, 0x100, v69
	s_branch .LBB0_595
.Las_v2_mini:
	s_waitcnt vmcnt(0) lgkmcnt(0)
	v_pk_fma_f32 v[70:71], v[2:3], v[78:79], v[70:71] op_sel_hi:[1,0,1]
	v_pk_fma_f32 v[76:77], v[0:1], v[78:79], v[76:77] op_sel_hi:[1,0,1]
	s_add_i32 s12, s12, 64
	v_add_u32_e32 v75, 0x100, v75
	s_branch .LBB0_629

; __device__ __forceinline__ void attn_sample(const Params& p, int j, LAS unsigned char* lds, int gw, int NGW, int wave, int lane) {
;     ...
;             for (int jj0 = 0; jj0 < 129; jj0 += 64) {
;                 f32x4 kv[16];
; #pragma unroll
;                 for (int u = 0; u < 16; ++u) { int jj = jj0 + u * 4 + rs; jj = jj > 128 ? 128 : jj; const int pos = W + t - (jj << dsh);
;                     kv[u] = *(const f32x4*)(pos >= W ? nbuf + (size_t)(pos - 8) * 1024 : cache + (size_t)pos * 1024); }
; #pragma unroll
;                 for (int u = 0; u < 16; ++u) { const int jj = jj0 + u * 4 + rs;
;                     const float d = row16_sum(kv[u][0] * qv[g][0] + kv[u][1] * qv[g][1] + kv[u][2] * qv[g][2] + kv[u][3] * qv[g][3]);
;                     if (jj <= 128) { mx = fmaxf(mx, d); if (ch == 0) scs[g * 129 + jj] = d; } }
.LBB0_394:
	v_add_u32_e32 v84, s52, v65
	v_add_u32_e32 v82, 64, v84
	v_min_i32_e32 v0, 0x80, v82
	v_lshlrev_b32_e32 v0, 2, v0
	v_sub_u32_e32 v0, s46, v0
	v_ashrrev_i32_e32 v1, 31, v0
	v_add_u32_e32 v2, -8, v0
	v_cmp_gt_i32_e32 vcc, s19, v0
	s_nop 1
	v_cndmask_b32_e32 v1, 0, v1, vcc
	v_cndmask_b32_e32 v0, v2, v0, vcc
	v_cndmask_b32_e32 v3, v81, v73, vcc
	v_cndmask_b32_e32 v2, v80, v72, vcc
	v_lshlrev_b64 v[0:1], 12, v[0:1]
	v_lshl_add_u64 v[0:1], v[2:3], 0, v[0:1]
	global_load_dwordx4 v[60:63], v[0:1], off
	s_cmp_eq_u32 s52, 64
	s_cbranch_scc1 .Las_k1_mini
	v_add_u32_e32 v0, 0x44, v84
	v_min_i32_e32 v0, 0x80, v0
	v_lshlrev_b32_e32 v0, 2, v0
	v_sub_u32_e32 v0, s46, v0
	v_ashrrev_i32_e32 v1, 31, v0
	v_add_u32_e32 v2, -8, v0
	v_cmp_gt_i32_e32 vcc, s19, v0
	s_waitcnt vmcnt(0)
	v_mul_f32_e32 v61, v79, v61
	v_cndmask_b32_e32 v1, 0, v1, vcc
	v_cndmask_b32_e32 v0, v2, v0, vcc
	v_cndmask_b32_e32 v3, v81, v73, vcc
	v_cndmask_b32_e32 v2, v80, v72, vcc
	v_lshlrev_b64 v[0:1], 12, v[0:1]
	v_lshl_add_u64 v[0:1], v[2:3], 0, v[0:1]
	global_load_dwordx4 v[56:59], v[0:1], off
	v_add_u32_e32 v0, 0x48, v84
	v_min_i32_e32 v0, 0x80, v0
	v_lshlrev_b32_e32 v0, 2, v0
	v_sub_u32_e32 v0, s46, v0
	v_ashrrev_i32_e32 v1, 31, v0
	v_add_u32_e32 v2, -8, v0
	v_cmp_gt_i32_e32 vcc, s19, v0
	v_fmac_f32_e32 v61, v78, v60
	v_fmac_f32_e32 v61, v76, v62
	v_cndmask_b32_e32 v1, 0, v1, vcc
	v_cndmask_b32_e32 v0, v2, v0, vcc
	v_cndmask_b32_e32 v3, v81, v73, vcc
	v_cndmask_b32_e32 v2, v80, v72, vcc
	v_lshlrev_b64 v[0:1], 12, v[0:1]
	v_lshl_add_u64 v[0:1], v[2:3], 0, v[0:1]
	global_load_dwordx4 v[52:55], v[0:1], off
	v_add_u32_e32 v0, 0x4c, v84
	v_min_i32_e32 v0, 0x80, v0
	v_lshlrev_b32_e32 v0, 2, v0
	v_sub_u32_e32 v0, s46, v0
	v_ashrrev_i32_e32 v1, 31, v0
	v_add_u32_e32 v2, -8, v0
	v_cmp_gt_i32_e32 vcc, s19, v0
	v_fmac_f32_e32 v61, v77, v63
	s_nop 0
	v_cndmask_b32_e32 v1, 0, v1, vcc
	v_cndmask_b32_e32 v0, v2, v0, vcc
	v_cndmask_b32_e32 v3, v81, v73, vcc
	v_cndmask_b32_e32 v2, v80, v72, vcc
	v_lshlrev_b64 v[0:1], 12, v[0:1]
	v_lshl_add_u64 v[0:1], v[2:3], 0, v[0:1]
	global_load_dwordx4 v[48:51], v[0:1], off
	v_add_u32_e32 v0, 0x50, v84
	v_min_i32_e32 v0, 0x80, v0
	v_lshlrev_b32_e32 v0, 2, v0
	v_sub_u32_e32 v0, s46, v0
	v_ashrrev_i32_e32 v1, 31, v0
	v_add_u32_e32 v2, -8, v0
	v_cmp_gt_i32_e32 vcc, s19, v0
	v_add_f32_dpp v60, v61, v61 row_ror:8 row_mask:0xf bank_mask:0xf bound_ctrl:1
	v_mov_b32_e32 v61, 0
	v_cndmask_b32_e32 v1, 0, v1, vcc
	v_cndmask_b32_e32 v0, v2, v0, vcc
	v_cndmask_b32_e32 v3, v81, v73, vcc
	v_cndmask_b32_e32 v2, v80, v72, vcc
	v_lshlrev_b64 v[0:1], 12, v[0:1]
	v_lshl_add_u64 v[0:1], v[2:3], 0, v[0:1]
	global_load_dwordx4 v[44:47], v[0:1], off
	v_add_u32_e32 v0, 0x54, v84
	v_min_i32_e32 v0, 0x80, v0
	v_lshlrev_b32_e32 v0, 2, v0
	v_sub_u32_e32 v0, s46, v0
	v_ashrrev_i32_e32 v1, 31, v0
	v_add_u32_e32 v2, -8, v0
	v_cmp_gt_i32_e32 vcc, s19, v0
	v_add_f32_dpp v60, v60, v60 row_ror:4 row_mask:0xf bank_mask:0xf bound_ctrl:1
	s_nop 0
	v_cndmask_b32_e32 v1, 0, v1, vcc
	v_cndmask_b32_e32 v0, v2, v0, vcc
	v_cndmask_b32_e32 v3, v81, v73, vcc
	v_cndmask_b32_e32 v2, v80, v72, vcc
	v_lshlrev_b64 v[0:1], 12, v[0:1]
	v_lshl_add_u64 v[0:1], v[2:3], 0, v[0:1]
	global_load_dwordx4 v[40:43], v[0:1], off
	v_add_u32_e32 v0, 0x58, v84
	v_min_i32_e32 v0, 0x80, v0
	v_lshlrev_b32_e32 v0, 2, v0
	v_sub_u32_e32 v0, s46, v0
	v_ashrrev_i32_e32 v1, 31, v0
	v_add_u32_e32 v2, -8, v0
	v_cmp_gt_i32_e32 vcc, s19, v0
	v_add_f32_dpp v60, v60, v60 row_ror:2 row_mask:0xf bank_mask:0xf bound_ctrl:1
	s_nop 0
	v_cndmask_b32_e32 v1, 0, v1, vcc
	v_cndmask_b32_e32 v0, v2, v0, vcc
	v_cndmask_b32_e32 v3, v81, v73, vcc
	v_cndmask_b32_e32 v2, v80, v72, vcc
	v_lshlrev_b64 v[0:1], 12, v[0:1]
	v_lshl_add_u64 v[0:1], v[2:3], 0, v[0:1]
	global_load_dwordx4 v[36:39], v[0:1], off
	v_add_u32_e32 v0, 0x5c, v84
	v_min_i32_e32 v0, 0x80, v0
	v_lshlrev_b32_e32 v0, 2, v0
	v_sub_u32_e32 v0, s46, v0
	v_ashrrev_i32_e32 v1, 31, v0
	v_add_u32_e32 v2, -8, v0
	v_cmp_gt_i32_e32 vcc, s19, v0
	v_mov_b32_dpp v61, v60 row_ror:1 row_mask:0xf bank_mask:0xf
	s_nop 0
	v_cndmask_b32_e32 v1, 0, v1, vcc
	v_cndmask_b32_e32 v0, v2, v0, vcc
	v_cndmask_b32_e32 v3, v81, v73, vcc
	v_cndmask_b32_e32 v2, v80, v72, vcc
; __device__ __forceinline__ void attn_sample(const Params& p, int j, LAS unsigned char* lds, int gw, int NGW, int wave, int lane) {
;     ...
;                 for (int u = 0; u < 16; ++u) { int jj = jj0 + u * 4 + rs; jj = jj > 128 ? 128 : jj; const int pos = W + t - (jj << dsh);
;                     kv[u] = *(const f32x4*)(pos >= W ? nbuf + (size_t)(pos - 8) * 1024 : cache + (size_t)pos * 1024); }
; #pragma unroll
;                 for (int u = 0; u < 16; ++u) { const int jj = jj0 + u * 4 + rs;
;                     const float d = row16_sum(kv[u][0] * qv[g][0] + kv[u][1] * qv[g][1] + kv[u][2] * qv[g][2] + kv[u][3] * qv[g][3]);
;                     if (jj <= 128) { mx = fmaxf(mx, d); if (ch == 0) scs[g * 129 + jj] = d; } }
	v_lshlrev_b64 v[0:1], 12, v[0:1]
	v_lshl_add_u64 v[0:1], v[2:3], 0, v[0:1]
	global_load_dwordx4 v[32:35], v[0:1], off
	v_add_u32_e32 v0, 0x60, v84
	v_min_i32_e32 v0, 0x80, v0
	v_lshlrev_b32_e32 v0, 2, v0
	v_sub_u32_e32 v0, s46, v0
	v_ashrrev_i32_e32 v1, 31, v0
	v_add_u32_e32 v2, -8, v0
	v_cmp_gt_i32_e32 vcc, s19, v0
	s_nop 1
	v_cndmask_b32_e32 v1, 0, v1, vcc
	v_cndmask_b32_e32 v0, v2, v0, vcc
	v_cndmask_b32_e32 v3, v81, v73, vcc
	v_cndmask_b32_e32 v2, v80, v72, vcc
	v_lshlrev_b64 v[0:1], 12, v[0:1]
	v_lshl_add_u64 v[0:1], v[2:3], 0, v[0:1]
	global_load_dwordx4 v[28:31], v[0:1], off
	v_add_u32_e32 v0, 0x64, v84
	v_min_i32_e32 v0, 0x80, v0
	v_lshlrev_b32_e32 v0, 2, v0
	v_sub_u32_e32 v0, s46, v0
	v_ashrrev_i32_e32 v1, 31, v0
	v_add_u32_e32 v2, -8, v0
	v_cmp_gt_i32_e32 vcc, s19, v0
	s_nop 1
	v_cndmask_b32_e32 v1, 0, v1, vcc
	v_cndmask_b32_e32 v0, v2, v0, vcc
	v_cndmask_b32_e32 v3, v81, v73, vcc
	v_cndmask_b32_e32 v2, v80, v72, vcc
	v_lshlrev_b64 v[0:1], 12, v[0:1]
	v_lshl_add_u64 v[0:1], v[2:3], 0, v[0:1]
	global_load_dwordx4 v[24:27], v[0:1], off
	v_add_u32_e32 v0, 0x68, v84
	v_min_i32_e32 v0, 0x80, v0
	v_lshlrev_b32_e32 v0, 2, v0
	v_sub_u32_e32 v0, s46, v0
	v_ashrrev_i32_e32 v1, 31, v0
	v_add_u32_e32 v2, -8, v0
	v_cmp_gt_i32_e32 vcc, s19, v0
	s_nop 1
	v_cndmask_b32_e32 v1, 0, v1, vcc
	v_cndmask_b32_e32 v0, v2, v0, vcc
	v_cndmask_b32_e32 v3, v81, v73, vcc
	v_cndmask_b32_e32 v2, v80, v72, vcc
	v_lshlrev_b64 v[0:1], 12, v[0:1]
	v_lshl_add_u64 v[0:1], v[2:3], 0, v[0:1]
	global_load_dwordx4 v[20:23], v[0:1], off
	v_add_u32_e32 v0, 0x6c, v84
	v_min_i32_e32 v0, 0x80, v0
	v_lshlrev_b32_e32 v0, 2, v0
	v_sub_u32_e32 v0, s46, v0
	v_ashrrev_i32_e32 v1, 31, v0
	v_add_u32_e32 v2, -8, v0
	v_cmp_gt_i32_e32 vcc, s19, v0
	s_nop 1
	v_cndmask_b32_e32 v1, 0, v1, vcc
	v_cndmask_b32_e32 v0, v2, v0, vcc
	v_cndmask_b32_e32 v3, v81, v73, vcc
	v_cndmask_b32_e32 v2, v80, v72, vcc
	v_lshlrev_b64 v[0:1], 12, v[0:1]
	v_lshl_add_u64 v[0:1], v[2:3], 0, v[0:1]
	global_load_dwordx4 v[16:19], v[0:1], off
	v_add_u32_e32 v0, 0x70, v84
	v_min_i32_e32 v0, 0x80, v0
	v_lshlrev_b32_e32 v0, 2, v0
	v_sub_u32_e32 v0, s46, v0
	v_ashrrev_i32_e32 v1, 31, v0
	v_add_u32_e32 v2, -8, v0
	v_cmp_gt_i32_e32 vcc, s19, v0
	s_nop 1
	v_cndmask_b32_e32 v1, 0, v1, vcc
	v_cndmask_b32_e32 v0, v2, v0, vcc
	v_cndmask_b32_e32 v3, v81, v73, vcc
	v_cndmask_b32_e32 v2, v80, v72, vcc
	v_lshlrev_b64 v[0:1], 12, v[0:1]
	v_lshl_add_u64 v[0:1], v[2:3], 0, v[0:1]
	global_load_dwordx4 v[12:15], v[0:1], off
	v_add_u32_e32 v0, 0x74, v84
	v_min_i32_e32 v0, 0x80, v0
	v_lshlrev_b32_e32 v0, 2, v0
	v_sub_u32_e32 v0, s46, v0
	v_ashrrev_i32_e32 v1, 31, v0
	v_add_u32_e32 v2, -8, v0
	v_cmp_gt_i32_e32 vcc, s19, v0
	s_nop 1
	v_cndmask_b32_e32 v1, 0, v1, vcc
	v_cndmask_b32_e32 v0, v2, v0, vcc
	v_cndmask_b32_e32 v3, v81, v73, vcc
	v_cndmask_b32_e32 v2, v80, v72, vcc
	v_lshlrev_b64 v[0:1], 12, v[0:1]
	v_lshl_add_u64 v[0:1], v[2:3], 0, v[0:1]
	global_load_dwordx4 v[8:11], v[0:1], off
	v_add_u32_e32 v0, 0x78, v84
	v_min_i32_e32 v0, 0x80, v0
	v_lshlrev_b32_e32 v0, 2, v0
	v_sub_u32_e32 v0, s46, v0
	v_ashrrev_i32_e32 v1, 31, v0
	v_add_u32_e32 v2, -8, v0
	v_cmp_gt_i32_e32 vcc, s19, v0
	s_nop 1
	v_cndmask_b32_e32 v1, 0, v1, vcc
	v_cndmask_b32_e32 v0, v2, v0, vcc
	v_cndmask_b32_e32 v3, v81, v73, vcc
	v_cndmask_b32_e32 v2, v80, v72, vcc
	v_lshlrev_b64 v[0:1], 12, v[0:1]
	v_lshl_add_u64 v[0:1], v[2:3], 0, v[0:1]
	global_load_dwordx4 v[4:7], v[0:1], off
	v_add_u32_e32 v0, 0x7c, v84
	v_min_i32_e32 v0, 0x80, v0
	v_lshlrev_b32_e32 v0, 2, v0
	v_sub_u32_e32 v0, s46, v0
	v_ashrrev_i32_e32 v1, 31, v0
	v_add_u32_e32 v2, -8, v0
	v_cmp_gt_i32_e32 vcc, s19, v0
	s_nop 1
	v_cndmask_b32_e32 v1, 0, v1, vcc
	v_cndmask_b32_e32 v0, v2, v0, vcc
	v_cndmask_b32_e32 v3, v81, v73, vcc
	v_cndmask_b32_e32 v2, v80, v72, vcc
	v_lshlrev_b64 v[0:1], 12, v[0:1]
	v_lshl_add_u64 v[0:1], v[2:3], 0, v[0:1]
	global_load_dwordx4 v[0:3], v[0:1], off
	v_cmp_gt_i32_e32 vcc, s35, v82
	s_and_saveexec_b64 s[30:31], vcc
	s_cbranch_execz .LBB0_398
	v_add_f32_e32 v60, v60, v61
	s_and_saveexec_b64 s[42:43], s[36:37]
	ds_write_b32 v69, v60
	s_or_b64 exec, exec, s[42:43]
	v_max_f32_e32 v61, v67, v67
	v_max_f32_e32 v67, v61, v60

; __device__ __forceinline__ void attn_sample(const Params& p, int j, LAS unsigned char* lds, int gw, int NGW, int wave, int lane) {
;     ...
;             for (int jj0 = 0; jj0 < 129; jj0 += 64) {
;                 f32x4 kv[16];
; #pragma unroll
;                 for (int u = 0; u < 16; ++u) { int jj = jj0 + u * 4 + rs; jj = jj > 128 ? 128 : jj; const int pos = W + t - (jj << dsh);
;                     kv[u] = *(const f32x4*)(pos >= W ? nbuf + (size_t)(pos - 8) * 1024 : cache + (size_t)pos * 1024); }
; #pragma unroll
;                 for (int u = 0; u < 16; ++u) { const int jj = jj0 + u * 4 + rs;
;                     const float d = row16_sum(kv[u][0] * qv[g][0] + kv[u][1] * qv[g][1] + kv[u][2] * qv[g][2] + kv[u][3] * qv[g][3]);
;                     if (jj <= 128) { mx = fmaxf(mx, d); if (ch == 0) scs[g * 129 + jj] = d; } }
.LBB0_460:
	v_add_u32_e32 v84, s42, v65
	v_add_u32_e32 v82, 64, v84
	v_min_i32_e32 v0, 0x80, v82
	v_lshlrev_b32_e32 v0, 4, v0
	v_sub_u32_e32 v0, s47, v0
	v_ashrrev_i32_e32 v1, 31, v0
	v_add_u32_e32 v2, -8, v0
	v_cmp_gt_i32_e32 vcc, s81, v0
	s_nop 1
	v_cndmask_b32_e32 v1, 0, v1, vcc
	v_cndmask_b32_e32 v0, v2, v0, vcc
	v_cndmask_b32_e32 v3, v81, v75, vcc
	v_cndmask_b32_e32 v2, v80, v74, vcc
	v_lshlrev_b64 v[0:1], 12, v[0:1]
	v_lshl_add_u64 v[0:1], v[2:3], 0, v[0:1]
	global_load_dwordx4 v[60:63], v[0:1], off
	s_cmp_eq_u32 s42, 64
	s_cbranch_scc1 .Las_k2_mini
	v_add_u32_e32 v0, 0x44, v84
	v_min_i32_e32 v0, 0x80, v0
	v_lshlrev_b32_e32 v0, 4, v0
	v_sub_u32_e32 v0, s47, v0
	v_ashrrev_i32_e32 v1, 31, v0
	v_add_u32_e32 v2, -8, v0
	v_cmp_gt_i32_e32 vcc, s81, v0
	s_waitcnt vmcnt(0)
	v_mul_f32_e32 v61, v79, v61
	v_cndmask_b32_e32 v1, 0, v1, vcc
	v_cndmask_b32_e32 v0, v2, v0, vcc
	v_cndmask_b32_e32 v3, v81, v75, vcc
	v_cndmask_b32_e32 v2, v80, v74, vcc
	v_lshlrev_b64 v[0:1], 12, v[0:1]
	v_lshl_add_u64 v[0:1], v[2:3], 0, v[0:1]
	global_load_dwordx4 v[56:59], v[0:1], off
	v_add_u32_e32 v0, 0x48, v84
	v_min_i32_e32 v0, 0x80, v0
	v_lshlrev_b32_e32 v0, 4, v0
	v_sub_u32_e32 v0, s47, v0
	v_ashrrev_i32_e32 v1, 31, v0
	v_add_u32_e32 v2, -8, v0
	v_cmp_gt_i32_e32 vcc, s81, v0
	v_fmac_f32_e32 v61, v78, v60
	v_fmac_f32_e32 v61, v76, v62
	v_cndmask_b32_e32 v1, 0, v1, vcc
	v_cndmask_b32_e32 v0, v2, v0, vcc
	v_cndmask_b32_e32 v3, v81, v75, vcc
	v_cndmask_b32_e32 v2, v80, v74, vcc
	v_lshlrev_b64 v[0:1], 12, v[0:1]
	v_lshl_add_u64 v[0:1], v[2:3], 0, v[0:1]
	global_load_dwordx4 v[52:55], v[0:1], off
	v_add_u32_e32 v0, 0x4c, v84
	v_min_i32_e32 v0, 0x80, v0
	v_lshlrev_b32_e32 v0, 4, v0
	v_sub_u32_e32 v0, s47, v0
	v_ashrrev_i32_e32 v1, 31, v0
	v_add_u32_e32 v2, -8, v0
	v_cmp_gt_i32_e32 vcc, s81, v0
	v_fmac_f32_e32 v61, v77, v63
	s_nop 0
	v_cndmask_b32_e32 v1, 0, v1, vcc
	v_cndmask_b32_e32 v0, v2, v0, vcc
	v_cndmask_b32_e32 v3, v81, v75, vcc
	v_cndmask_b32_e32 v2, v80, v74, vcc
	v_lshlrev_b64 v[0:1], 12, v[0:1]
	v_lshl_add_u64 v[0:1], v[2:3], 0, v[0:1]
	global_load_dwordx4 v[48:51], v[0:1], off
	v_add_u32_e32 v0, 0x50, v84
	v_min_i32_e32 v0, 0x80, v0
	v_lshlrev_b32_e32 v0, 4, v0
	v_sub_u32_e32 v0, s47, v0
	v_ashrrev_i32_e32 v1, 31, v0
	v_add_u32_e32 v2, -8, v0
	v_cmp_gt_i32_e32 vcc, s81, v0
	v_add_f32_dpp v60, v61, v61 row_ror:8 row_mask:0xf bank_mask:0xf bound_ctrl:1
	v_mov_b32_e32 v61, 0
	v_cndmask_b32_e32 v1, 0, v1, vcc
	v_cndmask_b32_e32 v0, v2, v0, vcc
	v_cndmask_b32_e32 v3, v81, v75, vcc
	v_cndmask_b32_e32 v2, v80, v74, vcc
	v_lshlrev_b64 v[0:1], 12, v[0:1]
	v_lshl_add_u64 v[0:1], v[2:3], 0, v[0:1]
	global_load_dwordx4 v[44:47], v[0:1], off
	v_add_u32_e32 v0, 0x54, v84
	v_min_i32_e32 v0, 0x80, v0
	v_lshlrev_b32_e32 v0, 4, v0
	v_sub_u32_e32 v0, s47, v0
	v_ashrrev_i32_e32 v1, 31, v0
	v_add_u32_e32 v2, -8, v0
	v_cmp_gt_i32_e32 vcc, s81, v0
	v_add_f32_dpp v60, v60, v60 row_ror:4 row_mask:0xf bank_mask:0xf bound_ctrl:1
	s_nop 0
	v_cndmask_b32_e32 v1, 0, v1, vcc
	v_cndmask_b32_e32 v0, v2, v0, vcc
	v_cndmask_b32_e32 v3, v81, v75, vcc
	v_cndmask_b32_e32 v2, v80, v74, vcc
	v_lshlrev_b64 v[0:1], 12, v[0:1]
	v_lshl_add_u64 v[0:1], v[2:3], 0, v[0:1]
	global_load_dwordx4 v[40:43], v[0:1], off
	v_add_u32_e32 v0, 0x58, v84
	v_min_i32_e32 v0, 0x80, v0
	v_lshlrev_b32_e32 v0, 4, v0
	v_sub_u32_e32 v0, s47, v0
	v_ashrrev_i32_e32 v1, 31, v0
	v_add_u32_e32 v2, -8, v0
	v_cmp_gt_i32_e32 vcc, s81, v0
	v_add_f32_dpp v60, v60, v60 row_ror:2 row_mask:0xf bank_mask:0xf bound_ctrl:1
	s_nop 0
	v_cndmask_b32_e32 v1, 0, v1, vcc
	v_cndmask_b32_e32 v0, v2, v0, vcc
	v_cndmask_b32_e32 v3, v81, v75, vcc
	v_cndmask_b32_e32 v2, v80, v74, vcc
	v_lshlrev_b64 v[0:1], 12, v[0:1]
	v_lshl_add_u64 v[0:1], v[2:3], 0, v[0:1]
	global_load_dwordx4 v[36:39], v[0:1], off
	v_add_u32_e32 v0, 0x5c, v84
	v_min_i32_e32 v0, 0x80, v0
	v_lshlrev_b32_e32 v0, 4, v0
	v_sub_u32_e32 v0, s47, v0
	v_ashrrev_i32_e32 v1, 31, v0
	v_add_u32_e32 v2, -8, v0
	v_cmp_gt_i32_e32 vcc, s81, v0
	v_mov_b32_dpp v61, v60 row_ror:1 row_mask:0xf bank_mask:0xf
	s_nop 0
	v_cndmask_b32_e32 v1, 0, v1, vcc
	v_cndmask_b32_e32 v0, v2, v0, vcc
	v_cndmask_b32_e32 v3, v81, v75, vcc
	v_cndmask_b32_e32 v2, v80, v74, vcc
; __device__ __forceinline__ void attn_sample(const Params& p, int j, LAS unsigned char* lds, int gw, int NGW, int wave, int lane) {
;     ...
;                 for (int u = 0; u < 16; ++u) { int jj = jj0 + u * 4 + rs; jj = jj > 128 ? 128 : jj; const int pos = W + t - (jj << dsh);
;                     kv[u] = *(const f32x4*)(pos >= W ? nbuf + (size_t)(pos - 8) * 1024 : cache + (size_t)pos * 1024); }
; #pragma unroll
;                 for (int u = 0; u < 16; ++u) { const int jj = jj0 + u * 4 + rs;
;                     const float d = row16_sum(kv[u][0] * qv[g][0] + kv[u][1] * qv[g][1] + kv[u][2] * qv[g][2] + kv[u][3] * qv[g][3]);
;                     if (jj <= 128) { mx = fmaxf(mx, d); if (ch == 0) scs[g * 129 + jj] = d; } }
	v_lshlrev_b64 v[0:1], 12, v[0:1]
	v_lshl_add_u64 v[0:1], v[2:3], 0, v[0:1]
	global_load_dwordx4 v[32:35], v[0:1], off
	v_add_u32_e32 v0, 0x60, v84
	v_min_i32_e32 v0, 0x80, v0
	v_lshlrev_b32_e32 v0, 4, v0
	v_sub_u32_e32 v0, s47, v0
	v_ashrrev_i32_e32 v1, 31, v0
	v_add_u32_e32 v2, -8, v0
	v_cmp_gt_i32_e32 vcc, s81, v0
	s_nop 1
	v_cndmask_b32_e32 v1, 0, v1, vcc
	v_cndmask_b32_e32 v0, v2, v0, vcc
	v_cndmask_b32_e32 v3, v81, v75, vcc
	v_cndmask_b32_e32 v2, v80, v74, vcc
	v_lshlrev_b64 v[0:1], 12, v[0:1]
	v_lshl_add_u64 v[0:1], v[2:3], 0, v[0:1]
	global_load_dwordx4 v[28:31], v[0:1], off
	v_add_u32_e32 v0, 0x64, v84
	v_min_i32_e32 v0, 0x80, v0
	v_lshlrev_b32_e32 v0, 4, v0
	v_sub_u32_e32 v0, s47, v0
	v_ashrrev_i32_e32 v1, 31, v0
	v_add_u32_e32 v2, -8, v0
	v_cmp_gt_i32_e32 vcc, s81, v0
	s_nop 1
	v_cndmask_b32_e32 v1, 0, v1, vcc
	v_cndmask_b32_e32 v0, v2, v0, vcc
	v_cndmask_b32_e32 v3, v81, v75, vcc
	v_cndmask_b32_e32 v2, v80, v74, vcc
	v_lshlrev_b64 v[0:1], 12, v[0:1]
	v_lshl_add_u64 v[0:1], v[2:3], 0, v[0:1]
	global_load_dwordx4 v[24:27], v[0:1], off
	v_add_u32_e32 v0, 0x68, v84
	v_min_i32_e32 v0, 0x80, v0
	v_lshlrev_b32_e32 v0, 4, v0
	v_sub_u32_e32 v0, s47, v0
	v_ashrrev_i32_e32 v1, 31, v0
	v_add_u32_e32 v2, -8, v0
	v_cmp_gt_i32_e32 vcc, s81, v0
	s_nop 1
	v_cndmask_b32_e32 v1, 0, v1, vcc
	v_cndmask_b32_e32 v0, v2, v0, vcc
	v_cndmask_b32_e32 v3, v81, v75, vcc
	v_cndmask_b32_e32 v2, v80, v74, vcc
	v_lshlrev_b64 v[0:1], 12, v[0:1]
	v_lshl_add_u64 v[0:1], v[2:3], 0, v[0:1]
	global_load_dwordx4 v[20:23], v[0:1], off
	v_add_u32_e32 v0, 0x6c, v84
	v_min_i32_e32 v0, 0x80, v0
	v_lshlrev_b32_e32 v0, 4, v0
	v_sub_u32_e32 v0, s47, v0
	v_ashrrev_i32_e32 v1, 31, v0
	v_add_u32_e32 v2, -8, v0
	v_cmp_gt_i32_e32 vcc, s81, v0
	s_nop 1
	v_cndmask_b32_e32 v1, 0, v1, vcc
	v_cndmask_b32_e32 v0, v2, v0, vcc
	v_cndmask_b32_e32 v3, v81, v75, vcc
	v_cndmask_b32_e32 v2, v80, v74, vcc
	v_lshlrev_b64 v[0:1], 12, v[0:1]
	v_lshl_add_u64 v[0:1], v[2:3], 0, v[0:1]
	global_load_dwordx4 v[16:19], v[0:1], off
	v_add_u32_e32 v0, 0x70, v84
	v_min_i32_e32 v0, 0x80, v0
	v_lshlrev_b32_e32 v0, 4, v0
	v_sub_u32_e32 v0, s47, v0
	v_ashrrev_i32_e32 v1, 31, v0
	v_add_u32_e32 v2, -8, v0
	v_cmp_gt_i32_e32 vcc, s81, v0
	s_nop 1
	v_cndmask_b32_e32 v1, 0, v1, vcc
	v_cndmask_b32_e32 v0, v2, v0, vcc
	v_cndmask_b32_e32 v3, v81, v75, vcc
	v_cndmask_b32_e32 v2, v80, v74, vcc
	v_lshlrev_b64 v[0:1], 12, v[0:1]
	v_lshl_add_u64 v[0:1], v[2:3], 0, v[0:1]
	global_load_dwordx4 v[12:15], v[0:1], off
	v_add_u32_e32 v0, 0x74, v84
	v_min_i32_e32 v0, 0x80, v0
	v_lshlrev_b32_e32 v0, 4, v0
	v_sub_u32_e32 v0, s47, v0
	v_ashrrev_i32_e32 v1, 31, v0
	v_add_u32_e32 v2, -8, v0
	v_cmp_gt_i32_e32 vcc, s81, v0
	s_nop 1
	v_cndmask_b32_e32 v1, 0, v1, vcc
	v_cndmask_b32_e32 v0, v2, v0, vcc
	v_cndmask_b32_e32 v3, v81, v75, vcc
	v_cndmask_b32_e32 v2, v80, v74, vcc
	v_lshlrev_b64 v[0:1], 12, v[0:1]
	v_lshl_add_u64 v[0:1], v[2:3], 0, v[0:1]
	global_load_dwordx4 v[8:11], v[0:1], off
	v_add_u32_e32 v0, 0x78, v84
	v_min_i32_e32 v0, 0x80, v0
	v_lshlrev_b32_e32 v0, 4, v0
	v_sub_u32_e32 v0, s47, v0
	v_ashrrev_i32_e32 v1, 31, v0
	v_add_u32_e32 v2, -8, v0
	v_cmp_gt_i32_e32 vcc, s81, v0
	s_nop 1
	v_cndmask_b32_e32 v1, 0, v1, vcc
	v_cndmask_b32_e32 v0, v2, v0, vcc
	v_cndmask_b32_e32 v3, v81, v75, vcc
	v_cndmask_b32_e32 v2, v80, v74, vcc
	v_lshlrev_b64 v[0:1], 12, v[0:1]
	v_lshl_add_u64 v[0:1], v[2:3], 0, v[0:1]
	global_load_dwordx4 v[4:7], v[0:1], off
	v_add_u32_e32 v0, 0x7c, v84
	v_min_i32_e32 v0, 0x80, v0
	v_lshlrev_b32_e32 v0, 4, v0
	v_sub_u32_e32 v0, s47, v0
	v_ashrrev_i32_e32 v1, 31, v0
	v_add_u32_e32 v2, -8, v0
	v_cmp_gt_i32_e32 vcc, s81, v0
	s_nop 1
	v_cndmask_b32_e32 v1, 0, v1, vcc
	v_cndmask_b32_e32 v0, v2, v0, vcc
	v_cndmask_b32_e32 v3, v81, v75, vcc
	v_cndmask_b32_e32 v2, v80, v74, vcc
	v_lshlrev_b64 v[0:1], 12, v[0:1]
	v_lshl_add_u64 v[0:1], v[2:3], 0, v[0:1]
	global_load_dwordx4 v[0:3], v[0:1], off
	v_cmp_gt_i32_e32 vcc, s35, v82
	s_and_saveexec_b64 s[24:25], vcc
	s_cbranch_execz .LBB0_464
	v_add_f32_e32 v60, v60, v61
	s_and_saveexec_b64 s[30:31], s[36:37]
	ds_write_b32 v69, v60
	s_or_b64 exec, exec, s[30:31]
	v_max_f32_e32 v61, v67, v67
	v_max_f32_e32 v67, v61, v60

; __device__ __forceinline__ void attn_sample(const Params& p, int j, LAS unsigned char* lds, int gw, int NGW, int wave, int lane) {
;     ...
;             for (int jj0 = 0; jj0 < 129; jj0 += 64) {
;                 f32x4 vv[16]; float pj[16];
; #pragma unroll
;                 for (int u = 0; u < 16; ++u) { int jj = jj0 + u * 4 + rs; const bool ok = jj <= 128; jj = ok ? jj : 128; const int pos = W + t - (jj << dsh);
;                     vv[u] = *(const f32x4*)(pos >= W ? nbuf + (size_t)(pos - 8) * 1024 : cache + (size_t)pos * 1024);
;                     pj[u] = ok ? scs[g * 129 + jj] : 0.f; }
; #pragma unroll
;                 for (int u = 0; u < 16; ++u) acc += vv[u] * pj[u];
.LBB0_529:
	v_add3_u32 v95, v65, s26, 64
	v_cmp_gt_i32_e32 vcc, s35, v95
	v_mov_b32_e32 v0, 0x80
	v_mov_b32_e32 v82, 0
	v_cndmask_b32_e32 v0, v0, v95, vcc
	v_sub_u32_e32 v0, s34, v0
	v_ashrrev_i32_e32 v1, 31, v0
	v_add_u32_e32 v2, -8, v0
	v_cmp_gt_i32_e64 s[42:43], s78, v0
	s_nop 1
	v_cndmask_b32_e64 v1, 0, v1, s[42:43]
	v_cndmask_b32_e64 v0, v2, v0, s[42:43]
	v_cndmask_b32_e64 v3, v81, v79, s[42:43]
	v_cndmask_b32_e64 v2, v80, v78, s[42:43]
	v_lshlrev_b64 v[0:1], 12, v[0:1]
	v_lshl_add_u64 v[0:1], v[2:3], 0, v[0:1]
	global_load_dwordx4 v[0:3], v[0:1], off
	s_and_saveexec_b64 s[24:25], vcc
	ds_read_b32 v82, v69
	s_or_b64 exec, exec, s[24:25]
	s_cmp_eq_u32 s26, 64
	s_cbranch_scc1 .Las_v0_mini
	v_min_i32_e32 v8, 0x7c, v95
	v_sub_u32_e32 v4, s34, v8
	v_add_u32_e32 v5, -4, v4
	v_add_u32_e32 v4, -12, v4
	v_cmp_gt_i32_e32 vcc, s78, v5
	v_mov_b32_e32 v84, 0
	v_mov_b32_e32 v86, 0
	v_cndmask_b32_e32 v184, v4, v5, vcc
	v_cndmask_b32_e32 v5, v81, v79, vcc
	v_cndmask_b32_e32 v4, v80, v78, vcc
	v_lshlrev_b64 v[6:7], 12, v[184:185]
	v_lshl_add_u64 v[4:5], v[4:5], 0, v[6:7]
	global_load_dwordx4 v[4:7], v[4:5], off
	v_cmp_gt_i32_e32 vcc, s54, v95
	s_and_saveexec_b64 s[24:25], vcc
	v_lshl_add_u32 v8, v8, 2, s7
	ds_read_b32 v86, v8 offset:40976
	s_or_b64 exec, exec, s[24:25]
	v_min_i32_e32 v12, 0x78, v95
	v_sub_u32_e32 v8, s34, v12
	v_add_u32_e32 v9, -8, v8
	v_add_u32_e32 v8, -16, v8
	v_cmp_gt_i32_e32 vcc, s78, v9
	s_nop 1
	v_cndmask_b32_e32 v184, v8, v9, vcc
	v_cndmask_b32_e32 v9, v81, v79, vcc
	v_cndmask_b32_e32 v8, v80, v78, vcc
	v_lshlrev_b64 v[10:11], 12, v[184:185]
	v_lshl_add_u64 v[8:9], v[8:9], 0, v[10:11]
	global_load_dwordx4 v[8:11], v[8:9], off
	v_cmp_gt_i32_e32 vcc, s1, v95
	s_and_saveexec_b64 s[24:25], vcc
	v_lshl_add_u32 v12, v12, 2, s7
	ds_read_b32 v84, v12 offset:40992
	s_or_b64 exec, exec, s[24:25]
	v_min_i32_e32 v16, 0x74, v95
	v_sub_u32_e32 v12, s34, v16
	v_add_u32_e32 v13, -12, v12
	v_subrev_u32_e32 v12, 20, v12
	v_cmp_gt_i32_e32 vcc, s78, v13
	v_mov_b32_e32 v88, 0
	v_mov_b32_e32 v90, 0
	v_cndmask_b32_e32 v184, v12, v13, vcc
	v_cndmask_b32_e32 v13, v81, v79, vcc
	v_cndmask_b32_e32 v12, v80, v78, vcc
	v_lshlrev_b64 v[14:15], 12, v[184:185]
	v_lshl_add_u64 v[12:13], v[12:13], 0, v[14:15]
	global_load_dwordx4 v[12:15], v[12:13], off
	v_cmp_gt_i32_e32 vcc, s14, v95
	s_and_saveexec_b64 s[24:25], vcc
	v_lshl_add_u32 v16, v16, 2, s7
	ds_read_b32 v90, v16 offset:41008
	s_or_b64 exec, exec, s[24:25]
	v_min_i32_e32 v20, 0x70, v95
	v_sub_u32_e32 v16, s34, v20
	v_add_u32_e32 v17, -16, v16
	v_subrev_u32_e32 v16, 24, v16
	v_cmp_gt_i32_e32 vcc, s78, v17
	s_nop 1
	v_cndmask_b32_e32 v184, v16, v17, vcc
	v_cndmask_b32_e32 v17, v81, v79, vcc
	v_cndmask_b32_e32 v16, v80, v78, vcc
	v_lshlrev_b64 v[18:19], 12, v[184:185]
	v_lshl_add_u64 v[16:17], v[16:17], 0, v[18:19]
	global_load_dwordx4 v[16:19], v[16:17], off
	v_cmp_gt_i32_e32 vcc, s55, v95
	s_and_saveexec_b64 s[24:25], vcc
	v_lshl_add_u32 v20, v20, 2, s7
	ds_read_b32 v88, v20 offset:41024
	s_or_b64 exec, exec, s[24:25]
	v_min_i32_e32 v24, 0x6c, v95
	v_sub_u32_e32 v20, s34, v24
	v_subrev_u32_e32 v21, 20, v20
	v_subrev_u32_e32 v20, 28, v20
	v_cmp_gt_i32_e32 vcc, s78, v21
	v_mov_b32_e32 v92, 0
	v_mov_b32_e32 v94, 0
	v_cndmask_b32_e32 v184, v20, v21, vcc
	v_cndmask_b32_e32 v21, v81, v79, vcc
	v_cndmask_b32_e32 v20, v80, v78, vcc
	v_lshlrev_b64 v[22:23], 12, v[184:185]
	v_lshl_add_u64 v[20:21], v[20:21], 0, v[22:23]
	global_load_dwordx4 v[20:23], v[20:21], off
	v_cmp_gt_i32_e32 vcc, s16, v95
	s_and_saveexec_b64 s[24:25], vcc
	v_lshl_add_u32 v24, v24, 2, s7
	ds_read_b32 v94, v24 offset:41040
	s_or_b64 exec, exec, s[24:25]
	v_min_i32_e32 v28, 0x68, v95
	v_sub_u32_e32 v24, s34, v28
	v_subrev_u32_e32 v25, 24, v24
	v_subrev_u32_e32 v24, 32, v24
	v_cmp_gt_i32_e32 vcc, s78, v25
	s_nop 1
	v_cndmask_b32_e32 v184, v24, v25, vcc
	v_cndmask_b32_e32 v25, v81, v79, vcc
	v_cndmask_b32_e32 v24, v80, v78, vcc
	v_lshlrev_b64 v[26:27], 12, v[184:185]
	v_lshl_add_u64 v[24:25], v[24:25], 0, v[26:27]
	global_load_dwordx4 v[24:27], v[24:25], off
	v_cmp_gt_i32_e32 vcc, s91, v95
	s_and_saveexec_b64 s[24:25], vcc
	v_lshl_add_u32 v28, v28, 2, s7
	ds_read_b32 v92, v28 offset:41056
	s_or_b64 exec, exec, s[24:25]
	v_min_i32_e32 v32, 0x64, v95
	v_sub_u32_e32 v28, s34, v32
	v_subrev_u32_e32 v29, 28, v28
	v_subrev_u32_e32 v28, 36, v28
	v_cmp_gt_i32_e32 vcc, s78, v29
	v_mov_b32_e32 v96, 0
	v_mov_b32_e32 v98, 0
	v_cndmask_b32_e32 v184, v28, v29, vcc
	v_cndmask_b32_e32 v29, v81, v79, vcc
	v_cndmask_b32_e32 v28, v80, v78, vcc
	v_lshlrev_b64 v[30:31], 12, v[184:185]
	v_lshl_add_u64 v[28:29], v[28:29], 0, v[30:31]
	global_load_dwordx4 v[28:31], v[28:29], off
	v_cmp_gt_i32_e32 vcc, s82, v95
	s_and_saveexec_b64 s[24:25], vcc
	v_lshl_add_u32 v32, v32, 2, s7
	ds_read_b32 v98, v32 offset:41072
; __device__ __forceinline__ void attn_sample(const Params& p, int j, LAS unsigned char* lds, int gw, int NGW, int wave, int lane) {
;     ...
;                 for (int u = 0; u < 16; ++u) { int jj = jj0 + u * 4 + rs; const bool ok = jj <= 128; jj = ok ? jj : 128; const int pos = W + t - (jj << dsh);
;                     vv[u] = *(const f32x4*)(pos >= W ? nbuf + (size_t)(pos - 8) * 1024 : cache + (size_t)pos * 1024);
;                     pj[u] = ok ? scs[g * 129 + jj] : 0.f; }
	s_or_b64 exec, exec, s[24:25]
	v_min_i32_e32 v36, 0x60, v95
	v_sub_u32_e32 v32, s34, v36
	v_subrev_u32_e32 v33, 32, v32
	v_subrev_u32_e32 v32, 40, v32
	v_cmp_gt_i32_e32 vcc, s78, v33
	s_nop 1
	v_cndmask_b32_e32 v184, v32, v33, vcc
	v_cndmask_b32_e32 v33, v81, v79, vcc
	v_cndmask_b32_e32 v32, v80, v78, vcc
	v_lshlrev_b64 v[34:35], 12, v[184:185]
	v_lshl_add_u64 v[32:33], v[32:33], 0, v[34:35]
	global_load_dwordx4 v[32:35], v[32:33], off
	v_cmp_gt_i32_e32 vcc, s79, v95
	s_and_saveexec_b64 s[24:25], vcc
	v_lshl_add_u32 v36, v36, 2, s7
	ds_read_b32 v96, v36 offset:41088
	s_or_b64 exec, exec, s[24:25]
	v_min_i32_e32 v40, 0x5c, v95
	v_sub_u32_e32 v36, s34, v40
	v_subrev_u32_e32 v37, 36, v36
	v_subrev_u32_e32 v36, 44, v36
	v_cmp_gt_i32_e32 vcc, s78, v37
	v_mov_b32_e32 v100, 0
	v_mov_b32_e32 v102, 0
	v_cndmask_b32_e32 v184, v36, v37, vcc
	v_cndmask_b32_e32 v37, v81, v79, vcc
	v_cndmask_b32_e32 v36, v80, v78, vcc
	v_lshlrev_b64 v[38:39], 12, v[184:185]
	v_lshl_add_u64 v[36:37], v[36:37], 0, v[38:39]
	global_load_dwordx4 v[36:39], v[36:37], off
	v_cmp_gt_i32_e32 vcc, s80, v95
	s_and_saveexec_b64 s[24:25], vcc
	v_lshl_add_u32 v40, v40, 2, s7
	ds_read_b32 v102, v40 offset:41104
	s_or_b64 exec, exec, s[24:25]
	v_min_i32_e32 v44, 0x58, v95
	v_sub_u32_e32 v40, s34, v44
	v_subrev_u32_e32 v41, 40, v40
	v_subrev_u32_e32 v40, 48, v40
	v_cmp_gt_i32_e32 vcc, s78, v41
	s_nop 1
	v_cndmask_b32_e32 v184, v40, v41, vcc
	v_cndmask_b32_e32 v41, v81, v79, vcc
	v_cndmask_b32_e32 v40, v80, v78, vcc
	v_lshlrev_b64 v[42:43], 12, v[184:185]
	v_lshl_add_u64 v[40:41], v[40:41], 0, v[42:43]
	global_load_dwordx4 v[40:43], v[40:41], off
	v_cmp_gt_i32_e32 vcc, s8, v95
	s_and_saveexec_b64 s[24:25], vcc
	v_lshl_add_u32 v44, v44, 2, s7
	ds_read_b32 v100, v44 offset:41120
	s_or_b64 exec, exec, s[24:25]
	v_min_i32_e32 v48, 0x54, v95
	v_sub_u32_e32 v44, s34, v48
	v_subrev_u32_e32 v45, 44, v44
	v_subrev_u32_e32 v44, 52, v44
	v_cmp_gt_i32_e32 vcc, s78, v45
	v_mov_b32_e32 v104, 0
	v_mov_b32_e32 v106, 0
	v_cndmask_b32_e32 v184, v44, v45, vcc
	v_cndmask_b32_e32 v45, v81, v79, vcc
	v_cndmask_b32_e32 v44, v80, v78, vcc
	v_lshlrev_b64 v[46:47], 12, v[184:185]
	v_lshl_add_u64 v[44:45], v[44:45], 0, v[46:47]
	global_load_dwordx4 v[44:47], v[44:45], off
	v_cmp_gt_i32_e32 vcc, s9, v95
	s_and_saveexec_b64 s[24:25], vcc
	v_lshl_add_u32 v48, v48, 2, s7
	ds_read_b32 v106, v48 offset:41136
	s_or_b64 exec, exec, s[24:25]
	v_min_i32_e32 v52, 0x50, v95
	v_sub_u32_e32 v48, s34, v52
	v_subrev_u32_e32 v49, 48, v48
	v_subrev_u32_e32 v48, 56, v48
	v_cmp_gt_i32_e32 vcc, s78, v49
	s_nop 1
	v_cndmask_b32_e32 v184, v48, v49, vcc
	v_cndmask_b32_e32 v49, v81, v79, vcc
	v_cndmask_b32_e32 v48, v80, v78, vcc
	v_lshlrev_b64 v[50:51], 12, v[184:185]
	v_lshl_add_u64 v[48:49], v[48:49], 0, v[50:51]
	global_load_dwordx4 v[48:51], v[48:49], off
	v_cmp_gt_i32_e32 vcc, s94, v95
	s_and_saveexec_b64 s[24:25], vcc
	v_lshl_add_u32 v52, v52, 2, s7
	ds_read_b32 v104, v52 offset:41152
	s_or_b64 exec, exec, s[24:25]
	v_min_i32_e32 v56, 0x4c, v95
	v_sub_u32_e32 v52, s34, v56
	v_subrev_u32_e32 v53, 52, v52
	v_subrev_u32_e32 v52, 60, v52
	v_cmp_gt_i32_e32 vcc, s78, v53
	v_mov_b32_e32 v108, 0
	v_mov_b32_e32 v110, 0
	v_cndmask_b32_e32 v184, v52, v53, vcc
	v_cndmask_b32_e32 v53, v81, v79, vcc
	v_cndmask_b32_e32 v52, v80, v78, vcc
	v_lshlrev_b64 v[54:55], 12, v[184:185]
	v_lshl_add_u64 v[52:53], v[52:53], 0, v[54:55]
	global_load_dwordx4 v[52:55], v[52:53], off
	v_cmp_gt_i32_e32 vcc, s95, v95
	s_and_saveexec_b64 s[24:25], vcc
	v_lshl_add_u32 v56, v56, 2, s7
	ds_read_b32 v110, v56 offset:41168
	s_or_b64 exec, exec, s[24:25]
	v_min_i32_e32 v60, 0x48, v95
	v_sub_u32_e32 v56, s34, v60
	v_subrev_u32_e32 v57, 56, v56
	v_subrev_u32_e32 v56, 64, v56
	v_cmp_gt_i32_e32 vcc, s78, v57
	s_nop 1
	v_cndmask_b32_e32 v184, v56, v57, vcc
	v_cndmask_b32_e32 v57, v81, v79, vcc
	v_cndmask_b32_e32 v56, v80, v78, vcc
	v_lshlrev_b64 v[58:59], 12, v[184:185]
	v_lshl_add_u64 v[56:57], v[56:57], 0, v[58:59]
	global_load_dwordx4 v[56:59], v[56:57], off
	v_cmp_gt_i32_e32 vcc, s10, v95
	s_and_saveexec_b64 s[24:25], vcc
	v_lshl_add_u32 v60, v60, 2, s7
	ds_read_b32 v108, v60 offset:41184
	s_or_b64 exec, exec, s[24:25]
	v_min_i32_e32 v97, 0x44, v95
	v_sub_u32_e32 v60, s34, v97
	v_subrev_u32_e32 v61, 60, v60
	v_add_u32_e32 v60, 0xffffffbc, v60
	v_cmp_gt_i32_e32 vcc, s78, v61
	v_mov_b32_e32 v112, 0
	s_nop 0
	v_cndmask_b32_e32 v184, v60, v61, vcc
	v_cndmask_b32_e32 v61, v81, v79, vcc
	v_cndmask_b32_e32 v60, v80, v78, vcc
	v_lshlrev_b64 v[62:63], 12, v[184:185]
	v_lshl_add_u64 v[60:61], v[60:61], 0, v[62:63]
	global_load_dwordx4 v[60:63], v[60:61], off
	v_cmp_gt_i32_e32 vcc, s11, v95
	s_and_saveexec_b64 s[24:25], vcc
	s_cbranch_execz .LBB0_528
	v_lshl_add_u32 v95, v97, 2, s7
	ds_read_b32 v112, v95 offset:41200
	s_branch .LBB0_528

; __device__ __forceinline__ void attn_sample(const Params& p, int j, LAS unsigned char* lds, int gw, int NGW, int wave, int lane) {
;     ...
;             for (int jj0 = 0; jj0 < 129; jj0 += 64) {
;                 f32x4 vv[16]; float pj[16];
; #pragma unroll
;                 for (int u = 0; u < 16; ++u) { int jj = jj0 + u * 4 + rs; const bool ok = jj <= 128; jj = ok ? jj : 128; const int pos = W + t - (jj << dsh);
;                     vv[u] = *(const f32x4*)(pos >= W ? nbuf + (size_t)(pos - 8) * 1024 : cache + (size_t)pos * 1024);
;                     pj[u] = ok ? scs[g * 129 + jj] : 0.f; }
; #pragma unroll
;                 for (int u = 0; u < 16; ++u) acc += vv[u] * pj[u];
.LBB0_563:
	v_add3_u32 v81, v65, s24, 64
	v_min_i32_e32 v0, 0x80, v81
	v_lshlrev_b32_e32 v0, 2, v0
	v_sub_u32_e32 v0, s46, v0
	v_ashrrev_i32_e32 v1, 31, v0
	v_add_u32_e32 v2, -8, v0
	v_cmp_gt_i32_e32 vcc, s19, v0
	v_mov_b32_e32 v80, 0
	v_mov_b32_e32 v82, 0
	v_cndmask_b32_e32 v1, 0, v1, vcc
	v_cndmask_b32_e32 v0, v2, v0, vcc
	v_cndmask_b32_e32 v3, v79, v73, vcc
	v_cndmask_b32_e32 v2, v78, v72, vcc
	v_lshlrev_b64 v[0:1], 12, v[0:1]
	v_lshl_add_u64 v[0:1], v[2:3], 0, v[0:1]
	global_load_dwordx4 v[0:3], v[0:1], off
	v_cmp_gt_i32_e32 vcc, s35, v81
	s_and_saveexec_b64 s[2:3], vcc
	ds_read_b32 v82, v69
	s_or_b64 exec, exec, s[2:3]
	s_cmp_eq_u32 s24, 64
	s_cbranch_scc1 .Las_v1_mini
	v_min_i32_e32 v8, 0x7c, v81
	v_lshlrev_b32_e32 v4, 2, v8
	v_sub_u32_e32 v4, s46, v4
	v_add_u32_e32 v6, -16, v4
	v_ashrrev_i32_e32 v5, 31, v6
	v_subrev_u32_e32 v4, 24, v4
	v_cmp_gt_i32_e32 vcc, s19, v6
	s_nop 1
	v_cndmask_b32_e32 v5, 0, v5, vcc
	v_cndmask_b32_e32 v4, v4, v6, vcc
	v_cndmask_b32_e32 v7, v79, v73, vcc
	v_cndmask_b32_e32 v6, v78, v72, vcc
	v_lshlrev_b64 v[4:5], 12, v[4:5]
	v_lshl_add_u64 v[4:5], v[6:7], 0, v[4:5]
	global_load_dwordx4 v[4:7], v[4:5], off
	v_cmp_gt_i32_e32 vcc, s54, v81
	s_and_saveexec_b64 s[2:3], vcc
	v_lshl_add_u32 v8, v8, 2, s7
	ds_read_b32 v80, v8 offset:41492
	s_or_b64 exec, exec, s[2:3]
	v_min_i32_e32 v12, 0x78, v81
	v_lshlrev_b32_e32 v8, 2, v12
	v_sub_u32_e32 v8, s46, v8
	v_subrev_u32_e32 v10, 32, v8
	v_ashrrev_i32_e32 v9, 31, v10
	v_subrev_u32_e32 v8, 40, v8
	v_cmp_gt_i32_e32 vcc, s19, v10
	v_mov_b32_e32 v84, 0
	v_mov_b32_e32 v86, 0
	v_cndmask_b32_e32 v9, 0, v9, vcc
	v_cndmask_b32_e32 v8, v8, v10, vcc
	v_cndmask_b32_e32 v11, v79, v73, vcc
	v_cndmask_b32_e32 v10, v78, v72, vcc
	v_lshlrev_b64 v[8:9], 12, v[8:9]
	v_lshl_add_u64 v[8:9], v[10:11], 0, v[8:9]
	global_load_dwordx4 v[8:11], v[8:9], off
	v_cmp_gt_i32_e32 vcc, s1, v81
	s_and_saveexec_b64 s[2:3], vcc
	v_lshl_add_u32 v12, v12, 2, s7
	ds_read_b32 v86, v12 offset:41508
	s_or_b64 exec, exec, s[2:3]
	v_min_i32_e32 v16, 0x74, v81
	v_lshlrev_b32_e32 v12, 2, v16
	v_sub_u32_e32 v12, s46, v12
	v_subrev_u32_e32 v14, 48, v12
	v_ashrrev_i32_e32 v13, 31, v14
	v_subrev_u32_e32 v12, 56, v12
	v_cmp_gt_i32_e32 vcc, s19, v14
	s_nop 1
	v_cndmask_b32_e32 v13, 0, v13, vcc
	v_cndmask_b32_e32 v12, v12, v14, vcc
	v_cndmask_b32_e32 v15, v79, v73, vcc
	v_cndmask_b32_e32 v14, v78, v72, vcc
	v_lshlrev_b64 v[12:13], 12, v[12:13]
	v_lshl_add_u64 v[12:13], v[14:15], 0, v[12:13]
	global_load_dwordx4 v[12:15], v[12:13], off
	v_cmp_gt_i32_e32 vcc, s14, v81
	s_and_saveexec_b64 s[2:3], vcc
	v_lshl_add_u32 v16, v16, 2, s7
	ds_read_b32 v84, v16 offset:41524
	s_or_b64 exec, exec, s[2:3]
	v_min_i32_e32 v20, 0x70, v81
	v_lshlrev_b32_e32 v16, 2, v20
	v_sub_u32_e32 v16, s46, v16
	v_subrev_u32_e32 v18, 64, v16
	v_ashrrev_i32_e32 v17, 31, v18
	v_add_u32_e32 v16, 0xffffffb8, v16
	v_cmp_gt_i32_e32 vcc, s19, v18
	v_mov_b32_e32 v88, 0
	v_mov_b32_e32 v90, 0
	v_cndmask_b32_e32 v17, 0, v17, vcc
	v_cndmask_b32_e32 v16, v16, v18, vcc
	v_cndmask_b32_e32 v19, v79, v73, vcc
	v_cndmask_b32_e32 v18, v78, v72, vcc
	v_lshlrev_b64 v[16:17], 12, v[16:17]
	v_lshl_add_u64 v[16:17], v[18:19], 0, v[16:17]
	global_load_dwordx4 v[16:19], v[16:17], off
	v_cmp_gt_i32_e32 vcc, s55, v81
	s_and_saveexec_b64 s[2:3], vcc
	v_lshl_add_u32 v20, v20, 2, s7
	ds_read_b32 v90, v20 offset:41540
	s_or_b64 exec, exec, s[2:3]
	v_min_i32_e32 v24, 0x6c, v81
	v_lshlrev_b32_e32 v20, 2, v24
	v_sub_u32_e32 v20, s46, v20
	v_add_u32_e32 v22, 0xffffffb0, v20
	v_ashrrev_i32_e32 v21, 31, v22
	v_add_u32_e32 v20, 0xffffffa8, v20
	v_cmp_gt_i32_e32 vcc, s19, v22
	s_nop 1
	v_cndmask_b32_e32 v21, 0, v21, vcc
	v_cndmask_b32_e32 v20, v20, v22, vcc
	v_cndmask_b32_e32 v23, v79, v73, vcc
	v_cndmask_b32_e32 v22, v78, v72, vcc
	v_lshlrev_b64 v[20:21], 12, v[20:21]
	v_lshl_add_u64 v[20:21], v[22:23], 0, v[20:21]
	global_load_dwordx4 v[20:23], v[20:21], off
	v_cmp_gt_i32_e32 vcc, s16, v81
	s_and_saveexec_b64 s[2:3], vcc
	v_lshl_add_u32 v24, v24, 2, s7
	ds_read_b32 v88, v24 offset:41556
	s_or_b64 exec, exec, s[2:3]
	v_min_i32_e32 v28, 0x68, v81
	v_lshlrev_b32_e32 v24, 2, v28
	v_sub_u32_e32 v24, s46, v24
	v_add_u32_e32 v26, 0xffffffa0, v24
	v_ashrrev_i32_e32 v25, 31, v26
	v_add_u32_e32 v24, 0xffffff98, v24
	v_cmp_gt_i32_e32 vcc, s19, v26
	v_mov_b32_e32 v92, 0
	v_mov_b32_e32 v94, 0
	v_cndmask_b32_e32 v25, 0, v25, vcc
	v_cndmask_b32_e32 v24, v24, v26, vcc
	v_cndmask_b32_e32 v27, v79, v73, vcc
	v_cndmask_b32_e32 v26, v78, v72, vcc
	v_lshlrev_b64 v[24:25], 12, v[24:25]
	v_lshl_add_u64 v[24:25], v[26:27], 0, v[24:25]
	global_load_dwordx4 v[24:27], v[24:25], off
	v_cmp_gt_i32_e32 vcc, s91, v81
	s_and_saveexec_b64 s[2:3], vcc
	v_lshl_add_u32 v28, v28, 2, s7
	ds_read_b32 v94, v28 offset:41572
	s_or_b64 exec, exec, s[2:3]
	v_min_i32_e32 v32, 0x64, v81
	v_lshlrev_b32_e32 v28, 2, v32
	v_sub_u32_e32 v28, s46, v28
	v_add_u32_e32 v30, 0xffffff90, v28
	v_ashrrev_i32_e32 v29, 31, v30
	v_add_u32_e32 v28, 0xffffff88, v28
	v_cmp_gt_i32_e32 vcc, s19, v30
	s_nop 1
	v_cndmask_b32_e32 v29, 0, v29, vcc
	v_cndmask_b32_e32 v28, v28, v30, vcc
	v_cndmask_b32_e32 v31, v79, v73, vcc
	v_cndmask_b32_e32 v30, v78, v72, vcc
	v_lshlrev_b64 v[28:29], 12, v[28:29]
	v_lshl_add_u64 v[28:29], v[30:31], 0, v[28:29]
	global_load_dwordx4 v[28:31], v[28:29], off
	v_cmp_gt_i32_e32 vcc, s82, v81
	s_and_saveexec_b64 s[2:3], vcc
	v_lshl_add_u32 v32, v32, 2, s7
	ds_read_b32 v92, v32 offset:41588
	s_or_b64 exec, exec, s[2:3]
	v_min_i32_e32 v36, 0x60, v81
	v_lshlrev_b32_e32 v32, 2, v36
	v_sub_u32_e32 v32, s46, v32
; __device__ __forceinline__ void attn_sample(const Params& p, int j, LAS unsigned char* lds, int gw, int NGW, int wave, int lane) {
;     ...
;                 for (int u = 0; u < 16; ++u) { int jj = jj0 + u * 4 + rs; const bool ok = jj <= 128; jj = ok ? jj : 128; const int pos = W + t - (jj << dsh);
;                     vv[u] = *(const f32x4*)(pos >= W ? nbuf + (size_t)(pos - 8) * 1024 : cache + (size_t)pos * 1024);
;                     pj[u] = ok ? scs[g * 129 + jj] : 0.f; }
	v_add_u32_e32 v34, 0xffffff80, v32
	v_ashrrev_i32_e32 v33, 31, v34
	v_add_u32_e32 v32, 0xffffff78, v32
	v_cmp_gt_i32_e32 vcc, s19, v34
	v_mov_b32_e32 v96, 0
	v_mov_b32_e32 v98, 0
	v_cndmask_b32_e32 v33, 0, v33, vcc
	v_cndmask_b32_e32 v32, v32, v34, vcc
	v_cndmask_b32_e32 v35, v79, v73, vcc
	v_cndmask_b32_e32 v34, v78, v72, vcc
	v_lshlrev_b64 v[32:33], 12, v[32:33]
	v_lshl_add_u64 v[32:33], v[34:35], 0, v[32:33]
	global_load_dwordx4 v[32:35], v[32:33], off
	v_cmp_gt_i32_e32 vcc, s79, v81
	s_and_saveexec_b64 s[2:3], vcc
	v_lshl_add_u32 v36, v36, 2, s7
	ds_read_b32 v98, v36 offset:41604
	s_or_b64 exec, exec, s[2:3]
	v_min_i32_e32 v40, 0x5c, v81
	v_lshlrev_b32_e32 v36, 2, v40
	v_sub_u32_e32 v36, s46, v36
	v_add_u32_e32 v38, 0xffffff70, v36
	v_ashrrev_i32_e32 v37, 31, v38
	v_add_u32_e32 v36, 0xffffff68, v36
	v_cmp_gt_i32_e32 vcc, s19, v38
	s_nop 1
	v_cndmask_b32_e32 v37, 0, v37, vcc
	v_cndmask_b32_e32 v36, v36, v38, vcc
	v_cndmask_b32_e32 v39, v79, v73, vcc
	v_cndmask_b32_e32 v38, v78, v72, vcc
	v_lshlrev_b64 v[36:37], 12, v[36:37]
	v_lshl_add_u64 v[36:37], v[38:39], 0, v[36:37]
	global_load_dwordx4 v[36:39], v[36:37], off
	v_cmp_gt_i32_e32 vcc, s80, v81
	s_and_saveexec_b64 s[2:3], vcc
	v_lshl_add_u32 v40, v40, 2, s7
	ds_read_b32 v96, v40 offset:41620
	s_or_b64 exec, exec, s[2:3]
	v_min_i32_e32 v44, 0x58, v81
	v_lshlrev_b32_e32 v40, 2, v44
	v_sub_u32_e32 v40, s46, v40
	v_add_u32_e32 v42, 0xffffff60, v40
	v_ashrrev_i32_e32 v41, 31, v42
	v_add_u32_e32 v40, 0xffffff58, v40
	v_cmp_gt_i32_e32 vcc, s19, v42
	v_mov_b32_e32 v100, 0
	v_mov_b32_e32 v102, 0
	v_cndmask_b32_e32 v41, 0, v41, vcc
	v_cndmask_b32_e32 v40, v40, v42, vcc
	v_cndmask_b32_e32 v43, v79, v73, vcc
	v_cndmask_b32_e32 v42, v78, v72, vcc
	v_lshlrev_b64 v[40:41], 12, v[40:41]
	v_lshl_add_u64 v[40:41], v[42:43], 0, v[40:41]
	global_load_dwordx4 v[40:43], v[40:41], off
	v_cmp_gt_i32_e32 vcc, s8, v81
	s_and_saveexec_b64 s[2:3], vcc
	v_lshl_add_u32 v44, v44, 2, s7
	ds_read_b32 v102, v44 offset:41636
	s_or_b64 exec, exec, s[2:3]
	v_min_i32_e32 v48, 0x54, v81
	v_lshlrev_b32_e32 v44, 2, v48
	v_sub_u32_e32 v44, s46, v44
	v_add_u32_e32 v46, 0xffffff50, v44
	v_ashrrev_i32_e32 v45, 31, v46
	v_add_u32_e32 v44, 0xffffff48, v44
	v_cmp_gt_i32_e32 vcc, s19, v46
	s_nop 1
	v_cndmask_b32_e32 v45, 0, v45, vcc
	v_cndmask_b32_e32 v44, v44, v46, vcc
	v_cndmask_b32_e32 v47, v79, v73, vcc
	v_cndmask_b32_e32 v46, v78, v72, vcc
	v_lshlrev_b64 v[44:45], 12, v[44:45]
	v_lshl_add_u64 v[44:45], v[46:47], 0, v[44:45]
	global_load_dwordx4 v[44:47], v[44:45], off
	v_cmp_gt_i32_e32 vcc, s9, v81
	s_and_saveexec_b64 s[2:3], vcc
	v_lshl_add_u32 v48, v48, 2, s7
	ds_read_b32 v100, v48 offset:41652
	s_or_b64 exec, exec, s[2:3]
	v_min_i32_e32 v52, 0x50, v81
	v_lshlrev_b32_e32 v48, 2, v52
	v_sub_u32_e32 v48, s46, v48
	v_add_u32_e32 v50, 0xffffff40, v48
	v_ashrrev_i32_e32 v49, 31, v50
	v_add_u32_e32 v48, 0xffffff38, v48
	v_cmp_gt_i32_e32 vcc, s19, v50
	v_mov_b32_e32 v104, 0
	v_mov_b32_e32 v106, 0
	v_cndmask_b32_e32 v49, 0, v49, vcc
	v_cndmask_b32_e32 v48, v48, v50, vcc
	v_cndmask_b32_e32 v51, v79, v73, vcc
	v_cndmask_b32_e32 v50, v78, v72, vcc
	v_lshlrev_b64 v[48:49], 12, v[48:49]
	v_lshl_add_u64 v[48:49], v[50:51], 0, v[48:49]
	global_load_dwordx4 v[48:51], v[48:49], off
	v_cmp_gt_i32_e32 vcc, s94, v81
	s_and_saveexec_b64 s[2:3], vcc
	v_lshl_add_u32 v52, v52, 2, s7
	ds_read_b32 v106, v52 offset:41668
	s_or_b64 exec, exec, s[2:3]
	v_min_i32_e32 v56, 0x4c, v81
	v_lshlrev_b32_e32 v52, 2, v56
	v_sub_u32_e32 v52, s46, v52
	v_add_u32_e32 v54, 0xffffff30, v52
	v_ashrrev_i32_e32 v53, 31, v54
	v_add_u32_e32 v52, 0xffffff28, v52
	v_cmp_gt_i32_e32 vcc, s19, v54
	s_nop 1
	v_cndmask_b32_e32 v53, 0, v53, vcc
	v_cndmask_b32_e32 v52, v52, v54, vcc
	v_cndmask_b32_e32 v55, v79, v73, vcc
	v_cndmask_b32_e32 v54, v78, v72, vcc
	v_lshlrev_b64 v[52:53], 12, v[52:53]
	v_lshl_add_u64 v[52:53], v[54:55], 0, v[52:53]
	global_load_dwordx4 v[52:55], v[52:53], off
	v_cmp_gt_i32_e32 vcc, s95, v81
	s_and_saveexec_b64 s[2:3], vcc
	v_lshl_add_u32 v56, v56, 2, s7
	ds_read_b32 v104, v56 offset:41684
	s_or_b64 exec, exec, s[2:3]
	v_min_i32_e32 v60, 0x48, v81
	v_lshlrev_b32_e32 v56, 2, v60
	v_sub_u32_e32 v56, s46, v56
	v_add_u32_e32 v58, 0xffffff20, v56
	v_ashrrev_i32_e32 v57, 31, v58
	v_add_u32_e32 v56, 0xffffff18, v56
	v_cmp_gt_i32_e32 vcc, s19, v58
	v_mov_b32_e32 v108, 0
	v_mov_b32_e32 v110, 0
	v_cndmask_b32_e32 v57, 0, v57, vcc
	v_cndmask_b32_e32 v56, v56, v58, vcc
	v_cndmask_b32_e32 v59, v79, v73, vcc
	v_cndmask_b32_e32 v58, v78, v72, vcc
	v_lshlrev_b64 v[56:57], 12, v[56:57]
	v_lshl_add_u64 v[56:57], v[58:59], 0, v[56:57]
	global_load_dwordx4 v[56:59], v[56:57], off
	v_cmp_gt_i32_e32 vcc, s10, v81
	s_and_saveexec_b64 s[2:3], vcc
	v_lshl_add_u32 v60, v60, 2, s7
	ds_read_b32 v110, v60 offset:41700
	s_or_b64 exec, exec, s[2:3]
	v_min_i32_e32 v95, 0x44, v81
	v_lshlrev_b32_e32 v60, 2, v95
	v_sub_u32_e32 v60, s46, v60
	v_add_u32_e32 v62, 0xffffff10, v60
	v_ashrrev_i32_e32 v61, 31, v62
	v_add_u32_e32 v60, 0xffffff08, v60
	v_cmp_gt_i32_e32 vcc, s19, v62
	s_nop 1
	v_cndmask_b32_e32 v61, 0, v61, vcc
	v_cndmask_b32_e32 v60, v60, v62, vcc
	v_cndmask_b32_e32 v63, v79, v73, vcc
	v_cndmask_b32_e32 v62, v78, v72, vcc
	v_lshlrev_b64 v[60:61], 12, v[60:61]
	v_lshl_add_u64 v[60:61], v[62:63], 0, v[60:61]
	global_load_dwordx4 v[60:63], v[60:61], off
	v_cmp_gt_i32_e32 vcc, s11, v81
	s_and_saveexec_b64 s[2:3], vcc
	s_cbranch_execz .LBB0_562
	v_lshl_add_u32 v81, v95, 2, s7
	ds_read_b32 v108, v81 offset:41716
	s_branch .LBB0_562

; __device__ __forceinline__ void attn_sample(const Params& p, int j, LAS unsigned char* lds, int gw, int NGW, int wave, int lane) {
;     ...
;             for (int jj0 = 0; jj0 < 129; jj0 += 64) {
;                 f32x4 vv[16]; float pj[16];
; #pragma unroll
;                 for (int u = 0; u < 16; ++u) { int jj = jj0 + u * 4 + rs; const bool ok = jj <= 128; jj = ok ? jj : 128; const int pos = W + t - (jj << dsh);
;                     vv[u] = *(const f32x4*)(pos >= W ? nbuf + (size_t)(pos - 8) * 1024 : cache + (size_t)pos * 1024);
;                     pj[u] = ok ? scs[g * 129 + jj] : 0.f; }
; #pragma unroll
;                 for (int u = 0; u < 16; ++u) acc += vv[u] * pj[u];
.LBB0_597:
	v_add3_u32 v79, v65, s12, 64
	v_min_i32_e32 v0, 0x80, v79
	v_lshlrev_b32_e32 v0, 4, v0
	v_sub_u32_e32 v0, s47, v0
	v_ashrrev_i32_e32 v1, 31, v0
	v_add_u32_e32 v2, -8, v0
	v_cmp_gt_i32_e32 vcc, s81, v0
	v_mov_b32_e32 v74, 0
	v_mov_b32_e32 v78, 0
	v_cndmask_b32_e32 v1, 0, v1, vcc
	v_cndmask_b32_e32 v0, v2, v0, vcc
	v_cndmask_b32_e32 v3, v69, v73, vcc
	v_cndmask_b32_e32 v2, v68, v72, vcc
	v_lshlrev_b64 v[0:1], 12, v[0:1]
	v_lshl_add_u64 v[0:1], v[2:3], 0, v[0:1]
	global_load_dwordx4 v[0:3], v[0:1], off
	v_cmp_gt_i32_e32 vcc, s35, v79
	s_and_saveexec_b64 s[2:3], vcc
	ds_read_b32 v78, v75
	s_or_b64 exec, exec, s[2:3]
	s_cmp_eq_u32 s12, 64
	s_cbranch_scc1 .Las_v2_mini
	v_min_i32_e32 v8, 0x7c, v79
	v_lshlrev_b32_e32 v4, 4, v8
	v_sub_u32_e32 v4, s47, v4
	v_subrev_u32_e32 v6, 64, v4
	v_ashrrev_i32_e32 v5, 31, v6
	v_add_u32_e32 v4, 0xffffffb8, v4
	v_cmp_gt_i32_e32 vcc, s81, v6
	s_nop 1
	v_cndmask_b32_e32 v5, 0, v5, vcc
	v_cndmask_b32_e32 v4, v4, v6, vcc
	v_cndmask_b32_e32 v7, v69, v73, vcc
	v_cndmask_b32_e32 v6, v68, v72, vcc
	v_lshlrev_b64 v[4:5], 12, v[4:5]
	v_lshl_add_u64 v[4:5], v[6:7], 0, v[4:5]
	global_load_dwordx4 v[4:7], v[4:5], off
	v_cmp_gt_i32_e32 vcc, s54, v79
	s_and_saveexec_b64 s[2:3], vcc
	v_lshl_add_u32 v8, v8, 2, s7
	ds_read_b32 v74, v8 offset:42008
	s_or_b64 exec, exec, s[2:3]
	v_min_i32_e32 v12, 0x78, v79
	v_lshlrev_b32_e32 v8, 4, v12
	v_sub_u32_e32 v8, s47, v8
	v_add_u32_e32 v10, 0xffffff80, v8
	v_ashrrev_i32_e32 v9, 31, v10
	v_add_u32_e32 v8, 0xffffff78, v8
	v_cmp_gt_i32_e32 vcc, s81, v10
	v_mov_b32_e32 v80, 0
	v_mov_b32_e32 v82, 0
	v_cndmask_b32_e32 v9, 0, v9, vcc
	v_cndmask_b32_e32 v8, v8, v10, vcc
	v_cndmask_b32_e32 v11, v69, v73, vcc
	v_cndmask_b32_e32 v10, v68, v72, vcc
	v_lshlrev_b64 v[8:9], 12, v[8:9]
	v_lshl_add_u64 v[8:9], v[10:11], 0, v[8:9]
	global_load_dwordx4 v[8:11], v[8:9], off
	v_cmp_gt_i32_e32 vcc, s1, v79
	s_and_saveexec_b64 s[2:3], vcc
	v_lshl_add_u32 v12, v12, 2, s7
	ds_read_b32 v82, v12 offset:42024
	s_or_b64 exec, exec, s[2:3]
	v_min_i32_e32 v16, 0x74, v79
	v_lshlrev_b32_e32 v12, 4, v16
	v_sub_u32_e32 v12, s47, v12
	v_add_u32_e32 v14, 0xffffff40, v12
	v_ashrrev_i32_e32 v13, 31, v14
	v_add_u32_e32 v12, 0xffffff38, v12
	v_cmp_gt_i32_e32 vcc, s81, v14
	s_nop 1
	v_cndmask_b32_e32 v13, 0, v13, vcc
	v_cndmask_b32_e32 v12, v12, v14, vcc
	v_cndmask_b32_e32 v15, v69, v73, vcc
	v_cndmask_b32_e32 v14, v68, v72, vcc
	v_lshlrev_b64 v[12:13], 12, v[12:13]
	v_lshl_add_u64 v[12:13], v[14:15], 0, v[12:13]
	global_load_dwordx4 v[12:15], v[12:13], off
	v_cmp_gt_i32_e32 vcc, s14, v79
	s_and_saveexec_b64 s[2:3], vcc
	v_lshl_add_u32 v16, v16, 2, s7
	ds_read_b32 v80, v16 offset:42040
	s_or_b64 exec, exec, s[2:3]
	v_min_i32_e32 v20, 0x70, v79
	v_lshlrev_b32_e32 v16, 4, v20
	v_sub_u32_e32 v16, s47, v16
	v_add_u32_e32 v18, 0xffffff00, v16
	v_ashrrev_i32_e32 v17, 31, v18
	v_add_u32_e32 v16, 0xfffffef8, v16
	v_cmp_gt_i32_e32 vcc, s81, v18
	v_mov_b32_e32 v84, 0
	v_mov_b32_e32 v86, 0
	v_cndmask_b32_e32 v17, 0, v17, vcc
	v_cndmask_b32_e32 v16, v16, v18, vcc
	v_cndmask_b32_e32 v19, v69, v73, vcc
	v_cndmask_b32_e32 v18, v68, v72, vcc
	v_lshlrev_b64 v[16:17], 12, v[16:17]
	v_lshl_add_u64 v[16:17], v[18:19], 0, v[16:17]
	global_load_dwordx4 v[16:19], v[16:17], off
	v_cmp_gt_i32_e32 vcc, s55, v79
	s_and_saveexec_b64 s[2:3], vcc
	v_lshl_add_u32 v20, v20, 2, s7
	ds_read_b32 v86, v20 offset:42056
	s_or_b64 exec, exec, s[2:3]
	v_min_i32_e32 v24, 0x6c, v79
	v_lshlrev_b32_e32 v20, 4, v24
	v_sub_u32_e32 v20, s47, v20
	v_add_u32_e32 v22, 0xfffffec0, v20
	v_ashrrev_i32_e32 v21, 31, v22
	v_add_u32_e32 v20, 0xfffffeb8, v20
	v_cmp_gt_i32_e32 vcc, s81, v22
	s_nop 1
	v_cndmask_b32_e32 v21, 0, v21, vcc
	v_cndmask_b32_e32 v20, v20, v22, vcc
	v_cndmask_b32_e32 v23, v69, v73, vcc
	v_cndmask_b32_e32 v22, v68, v72, vcc
	v_lshlrev_b64 v[20:21], 12, v[20:21]
	v_lshl_add_u64 v[20:21], v[22:23], 0, v[20:21]
	global_load_dwordx4 v[20:23], v[20:21], off
	v_cmp_gt_i32_e32 vcc, s16, v79
	s_and_saveexec_b64 s[2:3], vcc
	v_lshl_add_u32 v24, v24, 2, s7
	ds_read_b32 v84, v24 offset:42072
	s_or_b64 exec, exec, s[2:3]
	v_min_i32_e32 v28, 0x68, v79
	v_lshlrev_b32_e32 v24, 4, v28
	v_sub_u32_e32 v24, s47, v24
	v_add_u32_e32 v26, 0xfffffe80, v24
	v_ashrrev_i32_e32 v25, 31, v26
	v_add_u32_e32 v24, 0xfffffe78, v24
	v_cmp_gt_i32_e32 vcc, s81, v26
	v_mov_b32_e32 v88, 0
	v_mov_b32_e32 v90, 0
	v_cndmask_b32_e32 v25, 0, v25, vcc
	v_cndmask_b32_e32 v24, v24, v26, vcc
	v_cndmask_b32_e32 v27, v69, v73, vcc
	v_cndmask_b32_e32 v26, v68, v72, vcc
	v_lshlrev_b64 v[24:25], 12, v[24:25]
	v_lshl_add_u64 v[24:25], v[26:27], 0, v[24:25]
	global_load_dwordx4 v[24:27], v[24:25], off
	v_cmp_gt_i32_e32 vcc, s91, v79
	s_and_saveexec_b64 s[2:3], vcc
	v_lshl_add_u32 v28, v28, 2, s7
	ds_read_b32 v90, v28 offset:42088
	s_or_b64 exec, exec, s[2:3]
	v_min_i32_e32 v32, 0x64, v79
	v_lshlrev_b32_e32 v28, 4, v32
	v_sub_u32_e32 v28, s47, v28
	v_add_u32_e32 v30, 0xfffffe40, v28
	v_ashrrev_i32_e32 v29, 31, v30
	v_add_u32_e32 v28, 0xfffffe38, v28
	v_cmp_gt_i32_e32 vcc, s81, v30
	s_nop 1
	v_cndmask_b32_e32 v29, 0, v29, vcc
	v_cndmask_b32_e32 v28, v28, v30, vcc
	v_cndmask_b32_e32 v31, v69, v73, vcc
	v_cndmask_b32_e32 v30, v68, v72, vcc
	v_lshlrev_b64 v[28:29], 12, v[28:29]
	v_lshl_add_u64 v[28:29], v[30:31], 0, v[28:29]
	global_load_dwordx4 v[28:31], v[28:29], off
	v_cmp_gt_i32_e32 vcc, s82, v79
	s_and_saveexec_b64 s[2:3], vcc
	v_lshl_add_u32 v32, v32, 2, s7
	ds_read_b32 v88, v32 offset:42104
	s_or_b64 exec, exec, s[2:3]
	v_min_i32_e32 v36, 0x60, v79
	v_lshlrev_b32_e32 v32, 4, v36
; __device__ __forceinline__ void attn_sample(const Params& p, int j, LAS unsigned char* lds, int gw, int NGW, int wave, int lane) {
;     ...
;                 for (int u = 0; u < 16; ++u) { int jj = jj0 + u * 4 + rs; const bool ok = jj <= 128; jj = ok ? jj : 128; const int pos = W + t - (jj << dsh);
;                     vv[u] = *(const f32x4*)(pos >= W ? nbuf + (size_t)(pos - 8) * 1024 : cache + (size_t)pos * 1024);
;                     pj[u] = ok ? scs[g * 129 + jj] : 0.f; }
	v_sub_u32_e32 v32, s47, v32
	v_add_u32_e32 v34, 0xfffffe00, v32
	v_ashrrev_i32_e32 v33, 31, v34
	v_add_u32_e32 v32, 0xfffffdf8, v32
	v_cmp_gt_i32_e32 vcc, s81, v34
	v_mov_b32_e32 v92, 0
	v_mov_b32_e32 v94, 0
	v_cndmask_b32_e32 v33, 0, v33, vcc
	v_cndmask_b32_e32 v32, v32, v34, vcc
	v_cndmask_b32_e32 v35, v69, v73, vcc
	v_cndmask_b32_e32 v34, v68, v72, vcc
	v_lshlrev_b64 v[32:33], 12, v[32:33]
	v_lshl_add_u64 v[32:33], v[34:35], 0, v[32:33]
	global_load_dwordx4 v[32:35], v[32:33], off
	v_cmp_gt_i32_e32 vcc, s79, v79
	s_and_saveexec_b64 s[2:3], vcc
	v_lshl_add_u32 v36, v36, 2, s7
	ds_read_b32 v94, v36 offset:42120
	s_or_b64 exec, exec, s[2:3]
	v_min_i32_e32 v40, 0x5c, v79
	v_lshlrev_b32_e32 v36, 4, v40
	v_sub_u32_e32 v36, s47, v36
	v_add_u32_e32 v38, 0xfffffdc0, v36
	v_ashrrev_i32_e32 v37, 31, v38
	v_add_u32_e32 v36, 0xfffffdb8, v36
	v_cmp_gt_i32_e32 vcc, s81, v38
	s_nop 1
	v_cndmask_b32_e32 v37, 0, v37, vcc
	v_cndmask_b32_e32 v36, v36, v38, vcc
	v_cndmask_b32_e32 v39, v69, v73, vcc
	v_cndmask_b32_e32 v38, v68, v72, vcc
	v_lshlrev_b64 v[36:37], 12, v[36:37]
	v_lshl_add_u64 v[36:37], v[38:39], 0, v[36:37]
	global_load_dwordx4 v[36:39], v[36:37], off
	v_cmp_gt_i32_e32 vcc, s80, v79
	s_and_saveexec_b64 s[2:3], vcc
	v_lshl_add_u32 v40, v40, 2, s7
	ds_read_b32 v92, v40 offset:42136
	s_or_b64 exec, exec, s[2:3]
	v_min_i32_e32 v44, 0x58, v79
	v_lshlrev_b32_e32 v40, 4, v44
	v_sub_u32_e32 v40, s47, v40
	v_add_u32_e32 v42, 0xfffffd80, v40
	v_ashrrev_i32_e32 v41, 31, v42
	v_add_u32_e32 v40, 0xfffffd78, v40
	v_cmp_gt_i32_e32 vcc, s81, v42
	v_mov_b32_e32 v96, 0
	v_mov_b32_e32 v98, 0
	v_cndmask_b32_e32 v41, 0, v41, vcc
	v_cndmask_b32_e32 v40, v40, v42, vcc
	v_cndmask_b32_e32 v43, v69, v73, vcc
	v_cndmask_b32_e32 v42, v68, v72, vcc
	v_lshlrev_b64 v[40:41], 12, v[40:41]
	v_lshl_add_u64 v[40:41], v[42:43], 0, v[40:41]
	global_load_dwordx4 v[40:43], v[40:41], off
	v_cmp_gt_i32_e32 vcc, s8, v79
	s_and_saveexec_b64 s[2:3], vcc
	v_lshl_add_u32 v44, v44, 2, s7
	ds_read_b32 v98, v44 offset:42152
	s_or_b64 exec, exec, s[2:3]
	v_min_i32_e32 v48, 0x54, v79
	v_lshlrev_b32_e32 v44, 4, v48
	v_sub_u32_e32 v44, s47, v44
	v_add_u32_e32 v46, 0xfffffd40, v44
	v_ashrrev_i32_e32 v45, 31, v46
	v_add_u32_e32 v44, 0xfffffd38, v44
	v_cmp_gt_i32_e32 vcc, s81, v46
	s_nop 1
	v_cndmask_b32_e32 v45, 0, v45, vcc
	v_cndmask_b32_e32 v44, v44, v46, vcc
	v_cndmask_b32_e32 v47, v69, v73, vcc
	v_cndmask_b32_e32 v46, v68, v72, vcc
	v_lshlrev_b64 v[44:45], 12, v[44:45]
	v_lshl_add_u64 v[44:45], v[46:47], 0, v[44:45]
	global_load_dwordx4 v[44:47], v[44:45], off
	v_cmp_gt_i32_e32 vcc, s9, v79
	s_and_saveexec_b64 s[2:3], vcc
	v_lshl_add_u32 v48, v48, 2, s7
	ds_read_b32 v96, v48 offset:42168
	s_or_b64 exec, exec, s[2:3]
	v_min_i32_e32 v52, 0x50, v79
	v_lshlrev_b32_e32 v48, 4, v52
	v_sub_u32_e32 v48, s47, v48
	v_add_u32_e32 v50, 0xfffffd00, v48
	v_ashrrev_i32_e32 v49, 31, v50
	v_add_u32_e32 v48, 0xfffffcf8, v48
	v_cmp_gt_i32_e32 vcc, s81, v50
	v_mov_b32_e32 v100, 0
	v_mov_b32_e32 v102, 0
	v_cndmask_b32_e32 v49, 0, v49, vcc
	v_cndmask_b32_e32 v48, v48, v50, vcc
	v_cndmask_b32_e32 v51, v69, v73, vcc
	v_cndmask_b32_e32 v50, v68, v72, vcc
	v_lshlrev_b64 v[48:49], 12, v[48:49]
	v_lshl_add_u64 v[48:49], v[50:51], 0, v[48:49]
	global_load_dwordx4 v[48:51], v[48:49], off
	v_cmp_gt_i32_e32 vcc, s94, v79
	s_and_saveexec_b64 s[2:3], vcc
	v_lshl_add_u32 v52, v52, 2, s7
	ds_read_b32 v102, v52 offset:42184
	s_or_b64 exec, exec, s[2:3]
	v_min_i32_e32 v56, 0x4c, v79
	v_lshlrev_b32_e32 v52, 4, v56
	v_sub_u32_e32 v52, s47, v52
	v_add_u32_e32 v54, 0xfffffcc0, v52
	v_ashrrev_i32_e32 v53, 31, v54
	v_add_u32_e32 v52, 0xfffffcb8, v52
	v_cmp_gt_i32_e32 vcc, s81, v54
	s_nop 1
	v_cndmask_b32_e32 v53, 0, v53, vcc
	v_cndmask_b32_e32 v52, v52, v54, vcc
	v_cndmask_b32_e32 v55, v69, v73, vcc
	v_cndmask_b32_e32 v54, v68, v72, vcc
	v_lshlrev_b64 v[52:53], 12, v[52:53]
	v_lshl_add_u64 v[52:53], v[54:55], 0, v[52:53]
	global_load_dwordx4 v[52:55], v[52:53], off
	v_cmp_gt_i32_e32 vcc, s95, v79
	s_and_saveexec_b64 s[2:3], vcc
	v_lshl_add_u32 v56, v56, 2, s7
	ds_read_b32 v100, v56 offset:42200
	s_or_b64 exec, exec, s[2:3]
	v_min_i32_e32 v60, 0x48, v79
	v_lshlrev_b32_e32 v56, 4, v60
	v_sub_u32_e32 v56, s47, v56
	v_add_u32_e32 v58, 0xfffffc80, v56
	v_ashrrev_i32_e32 v57, 31, v58
	v_add_u32_e32 v56, 0xfffffc78, v56
	v_cmp_gt_i32_e32 vcc, s81, v58
	v_mov_b32_e32 v104, 0
	v_mov_b32_e32 v106, 0
	v_cndmask_b32_e32 v57, 0, v57, vcc
	v_cndmask_b32_e32 v56, v56, v58, vcc
	v_cndmask_b32_e32 v59, v69, v73, vcc
	v_cndmask_b32_e32 v58, v68, v72, vcc
	v_lshlrev_b64 v[56:57], 12, v[56:57]
	v_lshl_add_u64 v[56:57], v[58:59], 0, v[56:57]
	global_load_dwordx4 v[56:59], v[56:57], off
	v_cmp_gt_i32_e32 vcc, s10, v79
	s_and_saveexec_b64 s[2:3], vcc
	v_lshl_add_u32 v60, v60, 2, s7
	ds_read_b32 v106, v60 offset:42216
	s_or_b64 exec, exec, s[2:3]
	v_min_i32_e32 v81, 0x44, v79
	v_lshlrev_b32_e32 v60, 4, v81
	v_sub_u32_e32 v60, s47, v60
	v_add_u32_e32 v62, 0xfffffc40, v60
	v_ashrrev_i32_e32 v61, 31, v62
	v_add_u32_e32 v60, 0xfffffc38, v60
	v_cmp_gt_i32_e32 vcc, s81, v62
	s_nop 1
	v_cndmask_b32_e32 v61, 0, v61, vcc
	v_cndmask_b32_e32 v60, v60, v62, vcc
	v_cndmask_b32_e32 v63, v69, v73, vcc
	v_cndmask_b32_e32 v62, v68, v72, vcc
	v_lshlrev_b64 v[60:61], 12, v[60:61]
	v_lshl_add_u64 v[60:61], v[62:63], 0, v[60:61]
	global_load_dwordx4 v[60:63], v[60:61], off
	v_cmp_gt_i32_e32 vcc, s11, v79
	s_and_saveexec_b64 s[2:3], vcc
	s_cbranch_execz .LBB0_596
	v_lshl_add_u32 v79, v81, 2, s7
	ds_read_b32 v104, v79 offset:42232
	s_branch .LBB0_596
